# speedup vs baseline: 1.0119x; 1.0023x over previous
; __device__ __forceinline__ int v_rd_base(int lane) { return ((lane & 3) << 3) | (((lane >> 2) & 3) << 6) | (((lane >> 4) & 1) << 5) | (((lane >> 5) & 1) << 8); }
; __device__ __forceinline__ void attn_body256(const bf16_t* __restrict__ Qb, const bf16_t* __restrict__ Kh, const bf16_t* __restrict__ Vh,
;                                              bf16_t* Ob, int seq, unsigned char* lds, float lam, int MODE, bf16_t* Ab, const float* wsub) {
;     ...
;   unsigned koff[2], voff[4];
; #pragma unroll
;   for (int i = 0; i < 2; ++i) { const int o = i * 8192 + tid * 16; const int row = o >> 8; const int colB = (o & 255) ^ ((row & 7) << 4);
;     koff[i] = (unsigned)(row * LDK + (colB >> 1));
;     const int sub = o >> 9, kk = (sub >> 2) * 8 + ((o & 511) >> 6), c = (sub & 3) * 32 + (((o & 511) >> 1) & 31);
;     const int k = (kk & ~0xC) | ((kk & 4) << 1) | ((kk & 8) >> 1);
;     voff[i] = (unsigned)(k * LDK + c); voff[2 + i] = (unsigned)(k * LDK + 128 + c); }
;     ...
;   const int NT = seq / KVBLK;
;   A2_DMA(0, 0); A2_DMA(1, 1);
;   float m_reg = -1e30f, l_reg = 0; f32x16 o[8] = {}; bf16x8 qr[8];
;   const bf16_t* Qw = Qb + (long)(wid * QBLK + r32) * LDQ + hi * 8;
; #pragma unroll
;   for (int d0 = 0; d0 < 8; ++d0) qr[d0] = *reinterpret_cast<const bf16x8*>(Qw + d0 * 16);
;   const int vb0 = (int)(uintptr_t)lds + v_rd_base(lane);
;   asm volatile("s_waitcnt vmcnt(0)" ::: "memory"); __syncthreads();
; __global__ void __launch_bounds__(512, 2) fwd_megakernel(Params p) {
;     ...
;         for (int u2 = blockIdx.x * 2; u2 < 2048; u2 += (u2 & 1) ? (int)gridDim.x * 2 - 1 : 1) {
;           const int ul = u2 >> 1, pass = u2 & 1;
;           int u = ul;
;           if (gridDim.x == 256) { const int it = ul >> 8, bq = ul & 255; u = (it >> 1) * 512 + (bq & 7) * 64 + (bq >> 3) + 32 * (it & 1); }
;           int h, rows0, seqb, seq;
;           if (u < 512) { const int qb = u & 63; h = u >> 6; rows0 = qb * 256; seqb = 0; seq = 16384; }
;           else { const int u3 = u - 512, qb = u3 & 63; h = u3 >> 6; seqb = TP + (qb >> 3) * 2048; rows0 = seqb + (qb & 7) * 256; seq = 2048; }
;           const int n = 2 * h + pass;
;           att::attn_body256(R0 + (size_t)rows0 * DM + n * 128, R1 + (size_t)seqb * DM + n * 128, R2 + (size_t)seqb * DM + h * 256,
;                             Od + (size_t)rows0 * DM + h * 256, seq, smem, lam, pass, Abuf + (size_t)rows0 * DM + h * 256, p.in[14]);
.LBB0_669:
	s_and_b32 s2, s18, 1
	s_lshl_b64 s[10:11], s[62:63], 11
	s_lshl_b64 s[6:7], s[62:63], 12
	s_add_u32 s9, s96, s6
	s_addc_u32 s12, s97, s7
	s_lshl_b32 s16, s8, 8
	s_lshl_b32 s6, s2, 7
	s_or_b32 s6, s16, s6
	s_ashr_i32 s7, s6, 31
	s_lshl_b64 s[14:15], s[6:7], 1
	s_add_u32 s6, s9, s14
	s_addc_u32 s7, s12, s15
	s_lshl_b64 s[8:9], s[0:1], 1
	s_add_u32 s0, s60, s8
	s_addc_u32 s1, s53, s9
	s_add_u32 s12, s0, s14
	s_addc_u32 s13, s1, s15
	v_mov_b32 v16, v231
	v_lshrrev_b32_e32 v245, 7, v231
	v_lshlrev_b32_e32 v245, 3, v245
	v_bfe_u32 v244, v231, 1, 3
	v_add_u32_e32 v245, v245, v244
	v_lshlrev_b32_e32 v245, 11, v245
	v_bfe_u32 v244, v231, 4, 3
	v_lshl_add_u32 v245, v244, 4, v245
	v_and_b32_e32 v244, 1, v231
	v_lshl_add_u32 v245, v244, 3, v245
	s_add_u32 s20, s61, s8
	v_lshlrev_b32_e32 v17, 4, v16
	v_add_u32_e32 v6, 0x2000, v17
	s_addc_u32 s21, s68, s9
	s_ashr_i32 s17, s16, 31
	v_ashrrev_i32_e32 v8, 8, v6
	s_lshl_b64 s[0:1], s[16:17], 1
	v_and_b32_e32 v3, 0xf0, v17
	v_lshlrev_b32_e32 v6, 4, v8
	s_movk_i32 s26, 0x70
	s_add_u32 s16, s20, s0
	v_lshrrev_b32_e32 v0, 1, v16
	v_ashrrev_i32_e32 v2, 4, v16
	v_bitop3_b32 v3, v6, v3, s26 bitop3:0x6c
	s_addc_u32 s17, s21, s1
	v_readfirstlane_b32 s20, v16
	v_and_b32_e32 v22, 8, v0
	v_and_b32_e32 v0, 0x70, v16
	s_movk_i32 s21, 0xf0
	v_lshrrev_b32_e32 v4, 1, v2
	v_lshrrev_b32_e32 v3, 1, v3
	s_ashr_i32 s23, s20, 6
	v_bfe_u32 v18, v16, 2, 2
	v_lshlrev_b32_e32 v20, 3, v16
	v_bitop3_b32 v0, v17, v0, s21 bitop3:0x6c
	v_and_b32_e32 v4, 4, v4
	v_lshl_or_b32 v6, v8, 11, v3
	v_and_b32_e32 v3, 0x1ffff0, v8
	v_lshrrev_b32_e32 v8, 1, v8
	v_and_b32_e32 v19, 0x60, v16
	v_and_b32_e32 v21, 24, v20
	v_or_b32_e32 v7, v22, v18
	v_lshrrev_b32_e32 v0, 1, v0
	v_and_or_b32 v23, v2, -16, v4
	v_and_b32_e32 v8, 4, v8
	s_lshl_b32 s21, s23, 10
	v_or_b32_e32 v5, v21, v19
	v_lshl_or_b32 v0, v2, 11, v0
	v_or_b32_e32 v2, v7, v23
	v_or3_b32 v3, v3, v8, v7
	s_add_i32 s21, s21, 0
	v_lshl_or_b32 v2, v2, 11, v5
	v_mov_b32_e32 v2, v245
	v_lshlrev_b32_e32 v24, 11, v3
	s_add_i32 s22, s21, 0x10000
	v_lshlrev_b64 v[12:13], 1, v[0:1]
	v_mov_b32_e32 v3, v1
	v_or_b32_e32 v4, 0x80, v2
	v_lshl_add_u64 v[14:15], s[12:13], 0, v[12:13]
	s_mov_b32 m0, s22
	v_lshlrev_b64 v[2:3], 1, v[2:3]
	s_add_i32 s24, s21, 0x4000
	global_load_lds_dwordx4 v[14:15], off
	v_lshl_add_u64 v[14:15], s[16:17], 0, v[2:3]
	s_mov_b32 m0, s21
	s_mov_b64 s[30:31], 0x100
	v_mov_b32_e32 v7, v1
	s_and_b32 s20, s20, 0x3fffffc0
	v_or_b32_e32 v8, v24, v5
	v_add_u32_e32 v8, 0x10000, v245
	global_load_lds_dwordx4 v[14:15], off
	v_lshl_add_u64 v[14:15], v[14:15], 0, s[30:31]
	s_mov_b32 m0, s24
	v_lshlrev_b64 v[6:7], 1, v[6:7]
	v_mov_b32_e32 v9, v1
	s_lshl_b32 s20, s20, 2
	v_or_b32_e32 v10, 0x80, v8
	global_load_lds_dwordx4 v[14:15], off
	v_lshl_add_u64 v[14:15], s[12:13], 0, v[6:7]
	s_add_i32 m0, s21, 0x12000
	v_lshlrev_b64 v[8:9], 1, v[8:9]
	s_add_i32 s20, s20, 0
	global_load_lds_dwordx4 v[14:15], off
	v_lshl_add_u64 v[14:15], s[16:17], 0, v[8:9]
	s_add_i32 m0, s21, 0x2000
	s_add_i32 s20, s20, 0x18000
	global_load_lds_dwordx4 v[14:15], off
	s_add_i32 m0, s21, 0x6000
	s_add_u32 s12, s12, 0x40000
	s_addc_u32 s13, s13, 0
	v_lshl_add_u64 v[14:15], v[14:15], 0, s[30:31]
	s_add_u32 s16, s16, 0x40000
	global_load_lds_dwordx4 v[14:15], off
	s_addc_u32 s17, s17, 0
	s_add_i32 m0, s21, 0x14000
	s_add_i32 s24, s21, 0x8000
	v_lshl_add_u64 v[14:15], s[12:13], 0, v[12:13]
	v_mov_b32_e32 v5, v1
	s_add_i32 s25, s21, 0xc000
	global_load_lds_dwordx4 v[14:15], off
	v_lshl_add_u64 v[2:3], s[16:17], 0, v[2:3]
	s_mov_b32 m0, s24
	v_mov_b32_e32 v11, v1
	global_load_lds_dwordx4 v[2:3], off
	v_lshl_add_u64 v[2:3], v[4:5], 1, s[16:17]
	s_mov_b32 m0, s25
	v_and_b32_e32 v228, 31, v16
	global_load_lds_dwordx4 v[2:3], off
	v_lshl_add_u64 v[2:3], s[12:13], 0, v[6:7]
	s_add_i32 m0, s21, 0x16000
	s_lshl_b32 s12, s23, 5
	global_load_lds_dwordx4 v[2:3], off
	v_lshl_add_u64 v[2:3], s[16:17], 0, v[8:9]
	s_add_i32 m0, s21, 0xa000
	v_bfe_u32 v229, v16, 5, 1
	global_load_lds_dwordx4 v[2:3], off
	v_lshl_add_u64 v[2:3], v[10:11], 1, s[16:17]
	s_add_i32 m0, s21, 0xe000
	v_lshlrev_b32_e32 v0, 4, v229
	global_load_lds_dwordx4 v[2:3], off
	v_and_b32_e32 v2, 15, v231
	v_or_b32_e32 v2, s12, v2
	v_mov_b32_e32 v3, 0
	v_lshlrev_b64 v[2:3], 12, v[2:3]
	v_lshl_add_u64 v[2:3], s[6:7], 0, v[2:3]
	v_bfe_u32 v194, v231, 4, 2
	v_lshlrev_b32_e32 v194, 4, v194
	v_mov_b32_e32 v195, 0
	v_lshl_add_u64 v[2:3], v[2:3], 0, v[194:195]
	global_load_dwordx4 v[162:165], v[2:3], off
	global_load_dwordx4 v[166:169], v[2:3], off offset:64
	global_load_dwordx4 v[170:173], v[2:3], off offset:128
	global_load_dwordx4 v[174:177], v[2:3], off offset:192
	v_mov_b32_e32 v194, 0x10000
	v_lshl_add_u64 v[2:3], v[2:3], 0, v[194:195]
	global_load_dwordx4 v[178:181], v[2:3], off
	global_load_dwordx4 v[182:185], v[2:3], off offset:64
	global_load_dwordx4 v[186:189], v[2:3], off offset:128
	global_load_dwordx4 v[190:193], v[2:3], off offset:192
	v_and_b32_e32 v8, 0x70, v17
	s_movk_i32 s6, 0x60
	v_bitop3_b32 v236, v0, v8, s6 bitop3:0x36
	s_movk_i32 s6, 0x80
	v_bitop3_b32 v237, v0, v8, s6 bitop3:0x36
	s_movk_i32 s6, 0xa0
	v_bitop3_b32 v240, v0, v8, s6 bitop3:0x36
	s_movk_i32 s6, 0xc0
	s_cmp_lg_u32 0, -1
	v_and_b32_e32 v2, 63, v16
	v_lshlrev_b32_e32 v3, 1, v16
	v_and_b32_e32 v4, 0x118, v20
	v_bitop3_b32 v241, v0, v8, s6 bitop3:0x36
	s_movk_i32 s6, 0xe0
	s_cselect_b32 s16, 0, 0
	s_lshl_b32 s23, s19, 18
	v_and_b32_e32 v5, 0xc0, v17
	v_bitop3_b32 v247, v0, v8, s6 bitop3:0x36
	v_cmp_gt_u32_e64 s[6:7], 32, v2
	v_and_or_b32 v2, v3, 32, v4
	s_add_u32 s14, s8, s14
	v_add3_u32 v248, v5, s16, v2
	s_addc_u32 s15, s9, s15
	v_readlane_b32 s16, v254, 41
	s_add_u32 s14, s16, s14
	v_readlane_b32 s16, v254, 42
	s_addc_u32 s15, s16, s15
	s_add_u32 s8, s8, s0
	s_addc_u32 s9, s9, s1
	v_or3_b32 v2, v23, v22, v18
	v_lshlrev_b32_e32 v2, 11, v2
	s_add_u32 s8, s88, s8
	v_or3_b32 v2, v2, v19, v21
	v_mov_b32_e32 v2, v245
	v_mov_b32_e32 v3, v1
	s_addc_u32 s9, s89, s9
	s_waitcnt vmcnt(0)
; #define SBAR() __builtin_amdgcn_sched_barrier(0)
; __device__ __forceinline__ int v_rd_base(int lane) { return ((lane & 3) << 3) | (((lane >> 2) & 3) << 6) | (((lane >> 4) & 1) << 5) | (((lane >> 5) & 1) << 8); }
; __device__ __forceinline__ void qkt(f32x16& p0, f32x16& p1, const bf16_t* Ks, const bf16x8* qr, int r32, int hi) {
;   p0 = f32x16{}; p1 = f32x16{};
;   for (int d0 = 0; d0 < 8; ++d0) { int cb = (d0 * 16 + hi * 8) * 2;
;     bf16x8 b0 = *reinterpret_cast<const bf16x8*>((const char*)Ks + KSWZ(r32, cb));
;     bf16x8 b1 = *reinterpret_cast<const bf16x8*>((const char*)Ks + KSWZ(32 + r32, cb));
;     p0 = __builtin_amdgcn_mfma_f32_32x32x16_bf16(b0, qr[d0], p0, 0, 0, 0);
;     p1 = __builtin_amdgcn_mfma_f32_32x32x16_bf16(b1, qr[d0], p1, 0, 0, 0); }
; __device__ __forceinline__ void attn_body256(const bf16_t* __restrict__ Qb, const bf16_t* __restrict__ Kh, const bf16_t* __restrict__ Vh,
;                                              bf16_t* Ob, int seq, unsigned char* lds, float lam, int MODE, bf16_t* Ab, const float* wsub) {
;     ...
;   float m_reg = -1e30f, l_reg = 0; f32x16 o[8] = {}; bf16x8 qr[8];
;   const bf16_t* Qw = Qb + (long)(wid * QBLK + r32) * LDQ + hi * 8;
; #pragma unroll
;   for (int d0 = 0; d0 < 8; ++d0) qr[d0] = *reinterpret_cast<const bf16x8*>(Qw + d0 * 16);
;   const int vb0 = (int)(uintptr_t)lds + v_rd_base(lane);
;   asm volatile("s_waitcnt vmcnt(0)" ::: "memory"); __syncthreads();
;   for (int j = 0; j < NT; ++j) {
;     const int b = j & 1;
;     f32x16 p0, p1; float mn, alpha; bf16x8 pa0, pa1, pa2, pa3;
;     SBAR(); qkt(p0, p1, (const bf16_t*)(lds + A2_KOFF + b * A2_KBUF), qr, r32, hi);
	v_bitop3_b32 v232, v0, v17, s26 bitop3:0x78
	v_lshl_add_u64 v[224:225], v[2:3], 1, s[8:9]
	v_or3_b32 v2, v24, v19, v21
	v_add_u32_e32 v2, 0x10000, v245
	v_mov_b32_e32 v16, v1
	v_mov_b32_e32 v17, v1
	v_bitop3_b32 v233, v0, v8, 32 bitop3:0x36
	v_bitop3_b32 v234, v0, v8, 64 bitop3:0x36
	v_lshl_add_u64 v[220:221], s[14:15], 0, v[12:13]
	v_lshl_add_u64 v[222:223], s[14:15], 0, v[6:7]
	v_lshl_add_u64 v[226:227], v[2:3], 1, s[8:9]
	v_mov_b32_e32 v2, v1
	v_mov_b32_e32 v4, v1
	v_mov_b32_e32 v5, v1
	v_mov_b32_e32 v6, v1
	v_mov_b32_e32 v7, v1
	v_mov_b32_e32 v8, v1
	v_mov_b32_e32 v9, v1
	v_mov_b32_e32 v10, v1
	v_mov_b32_e32 v12, v1
	v_mov_b32_e32 v13, v1
	v_mov_b32_e32 v14, v1
	v_mov_b32_e32 v15, v1
	v_mov_b64_e32 v[128:129], v[16:17]
	v_mov_b64_e32 v[112:113], v[16:17]
	v_mov_b64_e32 v[96:97], v[16:17]
	v_mov_b64_e32 v[80:81], v[16:17]
	v_mov_b64_e32 v[64:65], v[16:17]
	v_mov_b64_e32 v[48:49], v[16:17]
	v_mov_b64_e32 v[32:33], v[16:17]
	s_mov_b32 s13, 2
	v_lshlrev_b32_e32 v230, 8, v228
	v_lshl_add_u32 v238, v228, 2, s20
	v_mov_b32_e32 v250, 0
	v_mov_b32_e32 v249, 0xf149f2ca
	s_mov_b64 s[14:15], 0
	v_mov_b64_e32 v[126:127], v[14:15]
	v_mov_b64_e32 v[124:125], v[12:13]
	v_mov_b64_e32 v[122:123], v[10:11]
	v_mov_b64_e32 v[120:121], v[8:9]
	v_mov_b64_e32 v[118:119], v[6:7]
	v_mov_b64_e32 v[116:117], v[4:5]
	v_mov_b64_e32 v[114:115], v[2:3]
	v_mov_b64_e32 v[110:111], v[14:15]
	v_mov_b64_e32 v[108:109], v[12:13]
	v_mov_b64_e32 v[106:107], v[10:11]
	v_mov_b64_e32 v[104:105], v[8:9]
	v_mov_b64_e32 v[102:103], v[6:7]
	v_mov_b64_e32 v[100:101], v[4:5]
	v_mov_b64_e32 v[98:99], v[2:3]
	v_mov_b64_e32 v[94:95], v[14:15]
	v_mov_b64_e32 v[92:93], v[12:13]
	v_mov_b64_e32 v[90:91], v[10:11]
	v_mov_b64_e32 v[88:89], v[8:9]
	v_mov_b64_e32 v[86:87], v[6:7]
	v_mov_b64_e32 v[84:85], v[4:5]
	v_mov_b64_e32 v[82:83], v[2:3]
	v_mov_b64_e32 v[78:79], v[14:15]
	v_mov_b64_e32 v[76:77], v[12:13]
	v_mov_b64_e32 v[74:75], v[10:11]
	v_mov_b64_e32 v[72:73], v[8:9]
	v_mov_b64_e32 v[70:71], v[6:7]
	v_mov_b64_e32 v[68:69], v[4:5]
	v_mov_b64_e32 v[66:67], v[2:3]
	v_mov_b64_e32 v[62:63], v[14:15]
	v_mov_b64_e32 v[60:61], v[12:13]
	v_mov_b64_e32 v[58:59], v[10:11]
	v_mov_b64_e32 v[56:57], v[8:9]
	v_mov_b64_e32 v[54:55], v[6:7]
	v_mov_b64_e32 v[52:53], v[4:5]
	v_mov_b64_e32 v[50:51], v[2:3]
	v_mov_b64_e32 v[46:47], v[14:15]
	v_mov_b64_e32 v[44:45], v[12:13]
	v_mov_b64_e32 v[42:43], v[10:11]
	v_mov_b64_e32 v[40:41], v[8:9]
	v_mov_b64_e32 v[38:39], v[6:7]
	v_mov_b64_e32 v[36:37], v[4:5]
	v_mov_b64_e32 v[34:35], v[2:3]
	v_mov_b64_e32 v[30:31], v[14:15]
	v_mov_b64_e32 v[28:29], v[12:13]
	v_mov_b64_e32 v[26:27], v[10:11]
	v_mov_b64_e32 v[24:25], v[8:9]
	v_mov_b64_e32 v[22:23], v[6:7]
	v_mov_b64_e32 v[20:21], v[4:5]
	v_mov_b64_e32 v[18:19], v[2:3]
	v_and_b32_e32 v237, 15, v231
	v_bfe_u32 v240, v231, 4, 2
	v_and_b32_e32 v241, 7, v237
	v_lshlrev_b32_e32 v241, 4, v241
	v_lshlrev_b32_e32 v247, 4, v240
	v_xor_b32_e32 v232, v247, v241
	v_add_u32_e32 v247, 64, v247
	v_xor_b32_e32 v233, v247, v241
	v_lshlrev_b32_e32 v247, 8, v237
	v_add_u32_e32 v232, v232, v247
	v_add_u32_e32 v233, v233, v247
	v_and_b32_e32 v247, 1, v240
	v_lshlrev_b32_e32 v248, 7, v247
	v_lshrrev_b32_e32 v247, 1, v240
	v_lshl_add_u32 v248, v247, 11, v248
	v_bfe_u32 v247, v231, 2, 2
	v_lshl_add_u32 v248, v247, 5, v248
	v_and_b32_e32 v247, 3, v231
	v_lshl_add_u32 v248, v247, 3, v248
	v_mov_b32_e32 v249, 0xf149f2ca
	v_mov_b32_e32 v246, 0xf149f2ca
	v_mov_b32_e32 v250, 0
	v_mov_b32_e32 v234, 0
	s_movk_i32 s62, 0x7fff
	s_waitcnt vmcnt(0) lgkmcnt(0)
	s_barrier
	s_mov_b32 s98, 0
	s_mov_b32 s99, 0x8000
	s_mov_b32 s100, 0x19000
	s_cmpk_ge_u32 s21, 0x1000
	s_cbranch_scc1 .Lat_y_qk
	s_mov_b32 s9, 0x10000
	v_add_u32_e32 v230, s9, v232
	v_add_u32_e32 v247, s9, v233
	ds_read_b128 v[194:197], v230
	ds_read_b128 v[198:201], v230 offset:4096
	ds_read_b128 v[202:205], v230 offset:8192
	ds_read_b128 v[206:209], v230 offset:12288
	ds_read_b128 v[210:213], v247
	ds_read_b128 v[214:217], v247 offset:4096
.Lat_x_top:
	s_add_i32 s8, s13, -2
	s_and_b32 s25, s8, 1
	s_lshl_b32 s24, s25, 14
	s_setprio 1
	s_waitcnt lgkmcnt(5)
	v_mfma_f32_16x16x32_bf16 v[130:133], v[194:197], v[162:165], 0
	v_mfma_f32_16x16x32_bf16 v[134:137], v[194:197], v[178:181], 0
	ds_read_b128 v[194:197], v247 offset:8192
	s_waitcnt lgkmcnt(5)
	v_mfma_f32_16x16x32_bf16 v[138:141], v[198:201], v[162:165], 0
	v_mfma_f32_16x16x32_bf16 v[142:145], v[198:201], v[178:181], 0
	ds_read_b128 v[198:201], v247 offset:12288
	s_waitcnt lgkmcnt(5)
	v_mfma_f32_16x16x32_bf16 v[146:149], v[202:205], v[162:165], 0
	v_mfma_f32_16x16x32_bf16 v[150:153], v[202:205], v[178:181], 0
	ds_read_b128 v[202:205], v230 offset:128
	s_waitcnt lgkmcnt(5)
	v_mfma_f32_16x16x32_bf16 v[154:157], v[206:209], v[162:165], 0
	v_mfma_f32_16x16x32_bf16 v[158:161], v[206:209], v[178:181], 0
	ds_read_b128 v[206:209], v230 offset:4224
	s_waitcnt lgkmcnt(5)
	v_mfma_f32_16x16x32_bf16 v[130:133], v[210:213], v[166:169], v[130:133]
	v_mfma_f32_16x16x32_bf16 v[134:137], v[210:213], v[182:185], v[134:137]
	ds_read_b128 v[210:213], v230 offset:8320
	s_waitcnt lgkmcnt(5)
	v_mfma_f32_16x16x32_bf16 v[138:141], v[214:217], v[166:169], v[138:141]
	v_mfma_f32_16x16x32_bf16 v[142:145], v[214:217], v[182:185], v[142:145]
	ds_read_b128 v[214:217], v230 offset:12416
	s_waitcnt lgkmcnt(5)
	v_mfma_f32_16x16x32_bf16 v[146:149], v[194:197], v[166:169], v[146:149]
	v_mfma_f32_16x16x32_bf16 v[150:153], v[194:197], v[182:185], v[150:153]
	ds_read_b128 v[194:197], v247 offset:128
	s_waitcnt lgkmcnt(5)
	v_mfma_f32_16x16x32_bf16 v[154:157], v[198:201], v[166:169], v[154:157]
	v_mfma_f32_16x16x32_bf16 v[158:161], v[198:201], v[182:185], v[158:161]
	ds_read_b128 v[198:201], v247 offset:4224
	s_waitcnt lgkmcnt(5)
; #define SBAR() __builtin_amdgcn_sched_barrier(0)
; __device__ __forceinline__ int crow(int r, int hi) { return (r & 3) + 8 * (r >> 2) + 4 * hi; }
; __device__ __forceinline__ int crow(int r, int hi) { return (r & 3) + 8 * (r >> 2) + 4 * hi; }
; __device__ __forceinline__ void partialSM(f32x16& p0, f32x16& p1, float& m_reg, float& mn, float& alpha) {
;   constexpr float C = SCALE * 1.4426950408889634f;
;   float pmax = p0[0]; for (int r = 1; r < 16; ++r) pmax = fmaxf(pmax, p0[r]); for (int r = 0; r < 16; ++r) pmax = fmaxf(pmax, p1[r]);
;   { auto rr = __builtin_amdgcn_permlane32_swap(__float_as_uint(pmax), __float_as_uint(pmax), false, false);
;     pmax = fmaxf(__uint_as_float(rr[0]), __uint_as_float(rr[1])); }
;   if (__builtin_expect(__all(pmax - m_reg <= THR / SCALE), 1)) { mn = m_reg; alpha = 1.f; }
;   else { mn = fmaxf(m_reg, pmax); alpha = __builtin_amdgcn_exp2f((m_reg - mn) * C); m_reg = mn; }
;   float mnC = -mn * C;
;   for (int r = 0; r < 16; ++r) p0[r] = fmaf(p0[r], C, mnC); for (int r = 0; r < 16; ++r) p1[r] = fmaf(p1[r], C, mnC);
;   for (int r = 0; r < 16; ++r) p0[r] = __builtin_amdgcn_exp2f(p0[r]);
; }
; __device__ __forceinline__ void attn_body256(const bf16_t* __restrict__ Qb, const bf16_t* __restrict__ Kh, const bf16_t* __restrict__ Vh,
;                                              bf16_t* Ob, int seq, unsigned char* lds, float lam, int MODE, bf16_t* Ab, const float* wsub) {
;     ...
;     SBAR(); qkt(p0, p1, (const bf16_t*)(lds + A2_KOFF + b * A2_KBUF), qr, r32, hi);
;     partialSM(p0, p1, m_reg, mn, alpha);
;     if (__any(alpha < 1.f)) { if (hi == 0) al_l[r32] = alpha; asm volatile("s_waitcnt lgkmcnt(0)" ::: "memory");
; #pragma unroll
;       for (int r = 0; r < 16; ++r) { const float a = al_l[crow(r, hi)];
; #pragma unroll
;         for (int d = 0; d < 8; ++d) o[d][r] *= a; } }
	v_mfma_f32_16x16x32_bf16 v[130:133], v[202:205], v[170:173], v[130:133]
	v_mfma_f32_16x16x32_bf16 v[134:137], v[202:205], v[186:189], v[134:137]
	ds_read_b128 v[202:205], v247 offset:8320
	s_waitcnt lgkmcnt(5)
	v_mfma_f32_16x16x32_bf16 v[138:141], v[206:209], v[170:173], v[138:141]
	v_mfma_f32_16x16x32_bf16 v[142:145], v[206:209], v[186:189], v[142:145]
	ds_read_b128 v[206:209], v247 offset:12416
	s_waitcnt lgkmcnt(5)
	v_mfma_f32_16x16x32_bf16 v[146:149], v[210:213], v[170:173], v[146:149]
	v_mfma_f32_16x16x32_bf16 v[150:153], v[210:213], v[186:189], v[150:153]
	s_waitcnt lgkmcnt(4)
	v_mfma_f32_16x16x32_bf16 v[154:157], v[214:217], v[170:173], v[154:157]
	v_mfma_f32_16x16x32_bf16 v[158:161], v[214:217], v[186:189], v[158:161]
	s_waitcnt lgkmcnt(3)
	v_mfma_f32_16x16x32_bf16 v[130:133], v[194:197], v[174:177], v[130:133]
	v_mfma_f32_16x16x32_bf16 v[134:137], v[194:197], v[190:193], v[134:137]
	s_waitcnt lgkmcnt(2)
	v_mfma_f32_16x16x32_bf16 v[138:141], v[198:201], v[174:177], v[138:141]
	v_mfma_f32_16x16x32_bf16 v[142:145], v[198:201], v[190:193], v[142:145]
	s_waitcnt lgkmcnt(1)
	v_mfma_f32_16x16x32_bf16 v[146:149], v[202:205], v[174:177], v[146:149]
	v_mfma_f32_16x16x32_bf16 v[150:153], v[202:205], v[190:193], v[150:153]
	s_waitcnt lgkmcnt(0)
	v_mfma_f32_16x16x32_bf16 v[154:157], v[206:209], v[174:177], v[154:157]
	v_mfma_f32_16x16x32_bf16 v[158:161], v[206:209], v[190:193], v[158:161]
	s_setprio 0
	s_nop 6
	v_max3_f32 v194, v130, v131, v132
	v_max3_f32 v194, v194, v133, v138
	v_max3_f32 v194, v194, v139, v140
	v_max3_f32 v194, v194, v141, v146
	v_max3_f32 v194, v194, v147, v148
	v_max3_f32 v194, v194, v149, v154
	v_max3_f32 v194, v194, v155, v156
	v_max_f32_e32 v194, v194, v157
	v_max3_f32 v195, v134, v135, v136
	v_max3_f32 v195, v195, v137, v142
	v_max3_f32 v195, v195, v143, v144
	v_max3_f32 v195, v195, v145, v150
	v_max3_f32 v195, v195, v151, v152
	v_max3_f32 v195, v195, v153, v158
	v_max3_f32 v195, v195, v159, v160
	v_max_f32_e32 v195, v195, v161
	v_mov_b32_e32 v196, v194
	v_mov_b32_e32 v197, v195
	s_nop 1
	v_permlane32_swap_b32_e32 v194, v196
	v_permlane32_swap_b32_e32 v195, v197
	v_max_f32_e32 v194, v194, v196
	v_max_f32_e32 v195, v195, v197
	v_mov_b32_e32 v196, v194
	v_mov_b32_e32 v197, v195
	s_nop 1
	v_permlane16_swap_b32_e32 v194, v196
	v_permlane16_swap_b32_e32 v195, v197
	v_max_f32_e32 v194, v194, v196
	v_max_f32_e32 v195, v195, v197
	v_sub_f32_e32 v196, v194, v249
	v_sub_f32_e32 v197, v195, v246
	v_max_f32_e32 v196, v196, v197
	v_cmp_ge_f32_e32 vcc, 0x42b504f3, v196
	v_max_f32_e32 v198, v249, v194
	v_max_f32_e32 v199, v246, v195
	v_sub_f32_e32 v196, v249, v198
	v_sub_f32_e32 v197, v246, v199
	v_mul_f32_e32 v196, 0x3e0293ee, v196
	v_mul_f32_e32 v197, 0x3e0293ee, v197
	v_exp_f32_e32 v196, v196
	v_exp_f32_e32 v197, v197
	s_cmp_eq_u64 vcc, exec
	s_cselect_b64 s[8:9], -1, 0
	v_cndmask_b32_e64 v236, v196, 1.0, s[8:9]
	v_cndmask_b32_e64 v240, v197, 1.0, s[8:9]
	v_cndmask_b32_e64 v249, v198, v249, s[8:9]
	v_cndmask_b32_e64 v246, v199, v246, s[8:9]
	s_cbranch_scc1 .Lat_x_noresc
	v_pk_mul_f32 v[2:3], v[2:3], v[236:237] op_sel_hi:[1,0]
	v_pk_mul_f32 v[4:5], v[4:5], v[236:237] op_sel_hi:[1,0]
	v_pk_mul_f32 v[6:7], v[6:7], v[240:241] op_sel_hi:[1,0]
	v_pk_mul_f32 v[8:9], v[8:9], v[240:241] op_sel_hi:[1,0]
	v_pk_mul_f32 v[10:11], v[10:11], v[236:237] op_sel_hi:[1,0]
	v_pk_mul_f32 v[12:13], v[12:13], v[236:237] op_sel_hi:[1,0]
	v_pk_mul_f32 v[14:15], v[14:15], v[240:241] op_sel_hi:[1,0]
	v_pk_mul_f32 v[16:17], v[16:17], v[240:241] op_sel_hi:[1,0]
	v_pk_mul_f32 v[114:115], v[114:115], v[236:237] op_sel_hi:[1,0]
	v_pk_mul_f32 v[116:117], v[116:117], v[236:237] op_sel_hi:[1,0]
	v_pk_mul_f32 v[118:119], v[118:119], v[240:241] op_sel_hi:[1,0]
	v_pk_mul_f32 v[120:121], v[120:121], v[240:241] op_sel_hi:[1,0]
	v_pk_mul_f32 v[122:123], v[122:123], v[236:237] op_sel_hi:[1,0]
	v_pk_mul_f32 v[124:125], v[124:125], v[236:237] op_sel_hi:[1,0]
	v_pk_mul_f32 v[126:127], v[126:127], v[240:241] op_sel_hi:[1,0]
	v_pk_mul_f32 v[128:129], v[128:129], v[240:241] op_sel_hi:[1,0]
	v_pk_mul_f32 v[98:99], v[98:99], v[236:237] op_sel_hi:[1,0]
	v_pk_mul_f32 v[100:101], v[100:101], v[236:237] op_sel_hi:[1,0]
	v_pk_mul_f32 v[102:103], v[102:103], v[240:241] op_sel_hi:[1,0]
	v_pk_mul_f32 v[104:105], v[104:105], v[240:241] op_sel_hi:[1,0]
	v_pk_mul_f32 v[106:107], v[106:107], v[236:237] op_sel_hi:[1,0]
	v_pk_mul_f32 v[108:109], v[108:109], v[236:237] op_sel_hi:[1,0]
	v_pk_mul_f32 v[110:111], v[110:111], v[240:241] op_sel_hi:[1,0]
	v_pk_mul_f32 v[112:113], v[112:113], v[240:241] op_sel_hi:[1,0]
	v_pk_mul_f32 v[82:83], v[82:83], v[236:237] op_sel_hi:[1,0]
	v_pk_mul_f32 v[84:85], v[84:85], v[236:237] op_sel_hi:[1,0]
	v_pk_mul_f32 v[86:87], v[86:87], v[240:241] op_sel_hi:[1,0]
	v_pk_mul_f32 v[88:89], v[88:89], v[240:241] op_sel_hi:[1,0]
	v_pk_mul_f32 v[90:91], v[90:91], v[236:237] op_sel_hi:[1,0]
	v_pk_mul_f32 v[92:93], v[92:93], v[236:237] op_sel_hi:[1,0]
	v_pk_mul_f32 v[94:95], v[94:95], v[240:241] op_sel_hi:[1,0]
	v_pk_mul_f32 v[96:97], v[96:97], v[240:241] op_sel_hi:[1,0]
	v_pk_mul_f32 v[66:67], v[66:67], v[236:237] op_sel_hi:[1,0]
	v_pk_mul_f32 v[68:69], v[68:69], v[236:237] op_sel_hi:[1,0]
	v_pk_mul_f32 v[70:71], v[70:71], v[240:241] op_sel_hi:[1,0]
	v_pk_mul_f32 v[72:73], v[72:73], v[240:241] op_sel_hi:[1,0]
	v_pk_mul_f32 v[74:75], v[74:75], v[236:237] op_sel_hi:[1,0]
	v_pk_mul_f32 v[76:77], v[76:77], v[236:237] op_sel_hi:[1,0]
	v_pk_mul_f32 v[78:79], v[78:79], v[240:241] op_sel_hi:[1,0]
	v_pk_mul_f32 v[80:81], v[80:81], v[240:241] op_sel_hi:[1,0]
	v_pk_mul_f32 v[50:51], v[50:51], v[236:237] op_sel_hi:[1,0]
	v_pk_mul_f32 v[52:53], v[52:53], v[236:237] op_sel_hi:[1,0]
	v_pk_mul_f32 v[54:55], v[54:55], v[240:241] op_sel_hi:[1,0]
	v_pk_mul_f32 v[56:57], v[56:57], v[240:241] op_sel_hi:[1,0]
	v_pk_mul_f32 v[58:59], v[58:59], v[236:237] op_sel_hi:[1,0]
	v_pk_mul_f32 v[60:61], v[60:61], v[236:237] op_sel_hi:[1,0]
	v_pk_mul_f32 v[62:63], v[62:63], v[240:241] op_sel_hi:[1,0]
	v_pk_mul_f32 v[64:65], v[64:65], v[240:241] op_sel_hi:[1,0]
	v_pk_mul_f32 v[34:35], v[34:35], v[236:237] op_sel_hi:[1,0]
	v_pk_mul_f32 v[36:37], v[36:37], v[236:237] op_sel_hi:[1,0]
	v_pk_mul_f32 v[38:39], v[38:39], v[240:241] op_sel_hi:[1,0]
	v_pk_mul_f32 v[40:41], v[40:41], v[240:241] op_sel_hi:[1,0]
	v_pk_mul_f32 v[42:43], v[42:43], v[236:237] op_sel_hi:[1,0]
	v_pk_mul_f32 v[44:45], v[44:45], v[236:237] op_sel_hi:[1,0]
	v_pk_mul_f32 v[46:47], v[46:47], v[240:241] op_sel_hi:[1,0]
	v_pk_mul_f32 v[48:49], v[48:49], v[240:241] op_sel_hi:[1,0]
	v_pk_mul_f32 v[18:19], v[18:19], v[236:237] op_sel_hi:[1,0]
	v_pk_mul_f32 v[20:21], v[20:21], v[236:237] op_sel_hi:[1,0]
	v_pk_mul_f32 v[22:23], v[22:23], v[240:241] op_sel_hi:[1,0]
	v_pk_mul_f32 v[24:25], v[24:25], v[240:241] op_sel_hi:[1,0]
	v_pk_mul_f32 v[26:27], v[26:27], v[236:237] op_sel_hi:[1,0]
	v_pk_mul_f32 v[28:29], v[28:29], v[236:237] op_sel_hi:[1,0]
	v_pk_mul_f32 v[30:31], v[30:31], v[240:241] op_sel_hi:[1,0]
	v_pk_mul_f32 v[32:33], v[32:33], v[240:241] op_sel_hi:[1,0]
; #define SBAR() __builtin_amdgcn_sched_barrier(0)
; __device__ __forceinline__ void partialSM(f32x16& p0, f32x16& p1, float& m_reg, float& mn, float& alpha) {
;     ...
;   for (int r = 0; r < 16; ++r) p0[r] = fmaf(p0[r], C, mnC); for (int r = 0; r < 16; ++r) p1[r] = fmaf(p1[r], C, mnC);
;   for (int r = 0; r < 16; ++r) p0[r] = __builtin_amdgcn_exp2f(p0[r]);
; }
; __device__ __forceinline__ void finishSM(f32x16& p0, f32x16& p1, float alpha, float& l_reg, bf16x8& pa0, bf16x8& pa1, bf16x8& pa2, bf16x8& pa3) {
;   for (int r = 0; r < 16; ++r) p1[r] = __builtin_amdgcn_exp2f(p1[r]);
;   float ps = 0; for (int r = 0; r < 16; ++r) ps += p0[r]; for (int r = 0; r < 16; ++r) ps += p1[r];
;   { auto rr = __builtin_amdgcn_permlane32_swap(__float_as_uint(ps), __float_as_uint(ps), false, false);
;     ps = __uint_as_float(rr[0]) + __uint_as_float(rr[1]); }
;   l_reg = l_reg * alpha + ps;
;     ...
;   PK4(p0, 0, pa0); PK4(p0, 8, pa1); PK4(p1, 0, pa2); PK4(p1, 8, pa3);
; template <int B> __device__ __forceinline__ void pv_reads(VFrag& f, int vb) {
;   constexpr int base = (B >> 2) * 16384 + (B & 3) * 512;
;   f.l0 = tr_read<base + 0 * 4096>(vb); f.h0 = tr_read<base + 0 * 4096 + 2048>(vb); f.l1 = tr_read<base + 1 * 4096>(vb); f.h1 = tr_read<base + 1 * 4096 + 2048>(vb);
;   f.l2 = tr_read<base + 2 * 4096>(vb); f.h2 = tr_read<base + 2 * 4096 + 2048>(vb); f.l3 = tr_read<base + 3 * 4096>(vb); f.h3 = tr_read<base + 3 * 4096 + 2048>(vb);
; }
; __device__ __forceinline__ void pv_mma(f32x16& od, const VFrag& f, bf16x8 pa0, bf16x8 pa1, bf16x8 pa2, bf16x8 pa3) {
;     ...
;   od = __builtin_amdgcn_mfma_f32_32x32x16_bf16(pa0, PKV(f.l0, f.h0), od, 0, 0, 0);
;   od = __builtin_amdgcn_mfma_f32_32x32x16_bf16(pa1, PKV(f.l1, f.h1), od, 0, 0, 0);
;   od = __builtin_amdgcn_mfma_f32_32x32x16_bf16(pa2, PKV(f.l2, f.h2), od, 0, 0, 0);
;   od = __builtin_amdgcn_mfma_f32_32x32x16_bf16(pa3, PKV(f.l3, f.h3), od, 0, 0, 0);
;     ...
; }
; __device__ __forceinline__ void pv_all(f32x16* o, int vb, bf16x8 pa0, bf16x8 pa1, bf16x8 pa2, bf16x8 pa3) {
;   VFrag fc, fn;
;   pv_reads<0>(fc, vb);
;   PV_STEP(0); PV_STEP(1); PV_STEP(2); PV_STEP(3); PV_STEP(4); PV_STEP(5); PV_STEP(6);
;   asm volatile("s_waitcnt lgkmcnt(0)" ::: "memory"); SBAR(); pv_mma(o[7], fc, pa0, pa1, pa2, pa3);
; }
.Lat_x_noresc:
	v_mul_f32_e32 v198, 0xbe0293ee, v249
	v_mul_f32_e32 v199, 0xbe0293ee, v246
	v_fmamk_f32 v130, v130, 0x3e0293ee, v198
	v_fmamk_f32 v131, v131, 0x3e0293ee, v198
	v_fmamk_f32 v132, v132, 0x3e0293ee, v198
	v_fmamk_f32 v133, v133, 0x3e0293ee, v198
	v_fmamk_f32 v134, v134, 0x3e0293ee, v199
	v_fmamk_f32 v135, v135, 0x3e0293ee, v199
	v_fmamk_f32 v136, v136, 0x3e0293ee, v199
	v_fmamk_f32 v137, v137, 0x3e0293ee, v199
	v_fmamk_f32 v138, v138, 0x3e0293ee, v198
	v_fmamk_f32 v139, v139, 0x3e0293ee, v198
	v_fmamk_f32 v140, v140, 0x3e0293ee, v198
	v_fmamk_f32 v141, v141, 0x3e0293ee, v198
	v_fmamk_f32 v142, v142, 0x3e0293ee, v199
	v_fmamk_f32 v143, v143, 0x3e0293ee, v199
	v_fmamk_f32 v144, v144, 0x3e0293ee, v199
	v_fmamk_f32 v145, v145, 0x3e0293ee, v199
	v_fmamk_f32 v146, v146, 0x3e0293ee, v198
	v_fmamk_f32 v147, v147, 0x3e0293ee, v198
	v_fmamk_f32 v148, v148, 0x3e0293ee, v198
	v_fmamk_f32 v149, v149, 0x3e0293ee, v198
	v_fmamk_f32 v150, v150, 0x3e0293ee, v199
	v_fmamk_f32 v151, v151, 0x3e0293ee, v199
	v_fmamk_f32 v152, v152, 0x3e0293ee, v199
	v_fmamk_f32 v153, v153, 0x3e0293ee, v199
	v_fmamk_f32 v154, v154, 0x3e0293ee, v198
	v_fmamk_f32 v155, v155, 0x3e0293ee, v198
	v_fmamk_f32 v156, v156, 0x3e0293ee, v198
	v_fmamk_f32 v157, v157, 0x3e0293ee, v198
	v_fmamk_f32 v158, v158, 0x3e0293ee, v199
	v_fmamk_f32 v159, v159, 0x3e0293ee, v199
	v_fmamk_f32 v160, v160, 0x3e0293ee, v199
	v_fmamk_f32 v161, v161, 0x3e0293ee, v199
	v_exp_f32_e32 v130, v130
	v_exp_f32_e32 v131, v131
	v_exp_f32_e32 v132, v132
	v_exp_f32_e32 v133, v133
	v_exp_f32_e32 v134, v134
	v_exp_f32_e32 v135, v135
	v_exp_f32_e32 v136, v136
	v_exp_f32_e32 v137, v137
	v_exp_f32_e32 v138, v138
	v_exp_f32_e32 v139, v139
	v_exp_f32_e32 v140, v140
	v_exp_f32_e32 v141, v141
	v_exp_f32_e32 v142, v142
	v_exp_f32_e32 v143, v143
	v_exp_f32_e32 v144, v144
	v_exp_f32_e32 v145, v145
	v_exp_f32_e32 v146, v146
	v_exp_f32_e32 v147, v147
	v_exp_f32_e32 v148, v148
	v_exp_f32_e32 v149, v149
	v_exp_f32_e32 v150, v150
	v_exp_f32_e32 v151, v151
	v_exp_f32_e32 v152, v152
	v_exp_f32_e32 v153, v153
	v_exp_f32_e32 v154, v154
	v_exp_f32_e32 v155, v155
	v_exp_f32_e32 v156, v156
	v_exp_f32_e32 v157, v157
	v_exp_f32_e32 v158, v158
	v_exp_f32_e32 v159, v159
	v_exp_f32_e32 v160, v160
	v_exp_f32_e32 v161, v161
	v_add_f32_e32 v194, v130, v131
	v_add_f32_e32 v194, v194, v132
	v_add_f32_e32 v194, v194, v133
	v_add_f32_e32 v194, v194, v138
	v_add_f32_e32 v194, v194, v139
	v_add_f32_e32 v194, v194, v140
	v_add_f32_e32 v194, v194, v141
	v_add_f32_e32 v194, v194, v146
	v_add_f32_e32 v194, v194, v147
	v_add_f32_e32 v194, v194, v148
	v_add_f32_e32 v194, v194, v149
	v_add_f32_e32 v194, v194, v154
	v_add_f32_e32 v194, v194, v155
	v_add_f32_e32 v194, v194, v156
	v_add_f32_e32 v194, v194, v157
	v_add_f32_e32 v195, v134, v135
	v_add_f32_e32 v195, v195, v136
	v_add_f32_e32 v195, v195, v137
	v_add_f32_e32 v195, v195, v142
	v_add_f32_e32 v195, v195, v143
	v_add_f32_e32 v195, v195, v144
	v_add_f32_e32 v195, v195, v145
	v_add_f32_e32 v195, v195, v150
	v_add_f32_e32 v195, v195, v151
	v_add_f32_e32 v195, v195, v152
	v_add_f32_e32 v195, v195, v153
	v_add_f32_e32 v195, v195, v158
	v_add_f32_e32 v195, v195, v159
	v_add_f32_e32 v195, v195, v160
	v_add_f32_e32 v195, v195, v161
	v_fma_f32 v250, v250, v236, v194
	v_fma_f32 v234, v234, v240, v195
	v_cvt_pk_bf16_f32 v130, v130, v131
	v_cvt_pk_bf16_f32 v131, v132, v133
	v_cvt_pk_bf16_f32 v132, v138, v139
	v_cvt_pk_bf16_f32 v133, v140, v141
	v_cvt_pk_bf16_f32 v134, v134, v135
	v_cvt_pk_bf16_f32 v135, v136, v137
	v_cvt_pk_bf16_f32 v136, v142, v143
	v_cvt_pk_bf16_f32 v137, v144, v145
	v_cvt_pk_bf16_f32 v138, v146, v147
	v_cvt_pk_bf16_f32 v139, v148, v149
	v_cvt_pk_bf16_f32 v140, v154, v155
	v_cvt_pk_bf16_f32 v141, v156, v157
	v_cvt_pk_bf16_f32 v142, v150, v151
	v_cvt_pk_bf16_f32 v143, v152, v153
	v_cvt_pk_bf16_f32 v144, v158, v159
	v_cvt_pk_bf16_f32 v145, v160, v161
	v_add_u32_e32 v244, s98, v248
	ds_read_b64_tr_b16 v[146:147], v244
	ds_read_b64_tr_b16 v[148:149], v244 offset:4096
	ds_read_b64_tr_b16 v[150:151], v244 offset:8192
	ds_read_b64_tr_b16 v[152:153], v244 offset:12288
	ds_read_b64_tr_b16 v[154:155], v244 offset:256
	ds_read_b64_tr_b16 v[156:157], v244 offset:4352
	ds_read_b64_tr_b16 v[158:159], v244 offset:8448
	ds_read_b64_tr_b16 v[160:161], v244 offset:12544
	ds_read_b64_tr_b16 v[194:195], v244 offset:512
	ds_read_b64_tr_b16 v[196:197], v244 offset:4608
	ds_read_b64_tr_b16 v[198:199], v244 offset:8704
	ds_read_b64_tr_b16 v[200:201], v244 offset:12800
	s_waitcnt lgkmcnt(8)
	v_mfma_f32_16x16x32_bf16 v[2:5], v[146:149], v[130:133], v[2:5]
	v_mfma_f32_16x16x32_bf16 v[6:9], v[146:149], v[134:137], v[6:9]
	v_mfma_f32_16x16x32_bf16 v[2:5], v[150:153], v[138:141], v[2:5]
	v_mfma_f32_16x16x32_bf16 v[6:9], v[150:153], v[142:145], v[6:9]
	ds_read_b64_tr_b16 v[146:147], v244 offset:768
	ds_read_b64_tr_b16 v[148:149], v244 offset:4864
	ds_read_b64_tr_b16 v[150:151], v244 offset:8960
	ds_read_b64_tr_b16 v[152:153], v244 offset:13056
	s_waitcnt lgkmcnt(8)
	v_mfma_f32_16x16x32_bf16 v[10:13], v[154:157], v[130:133], v[10:13]
	v_mfma_f32_16x16x32_bf16 v[14:17], v[154:157], v[134:137], v[14:17]
	v_mfma_f32_16x16x32_bf16 v[10:13], v[158:161], v[138:141], v[10:13]
	v_mfma_f32_16x16x32_bf16 v[14:17], v[158:161], v[142:145], v[14:17]
	ds_read_b64_tr_b16 v[154:155], v244 offset:1024
	ds_read_b64_tr_b16 v[156:157], v244 offset:5120
	ds_read_b64_tr_b16 v[158:159], v244 offset:9216
	ds_read_b64_tr_b16 v[160:161], v244 offset:13312
	s_waitcnt lgkmcnt(8)
; #define SBAR() __builtin_amdgcn_sched_barrier(0)
; #define PV_STEP(B) do { pv_reads<(B) + 1>(fn, vb); asm volatile("s_waitcnt lgkmcnt(8)" ::: "memory"); SBAR(); pv_mma(o[B], fc, pa0, pa1, pa2, pa3); SBAR(); fc = fn; } while (0)
; template <int B> __device__ __forceinline__ void pv_reads(VFrag& f, int vb) {
;   constexpr int base = (B >> 2) * 16384 + (B & 3) * 512;
;   f.l0 = tr_read<base + 0 * 4096>(vb); f.h0 = tr_read<base + 0 * 4096 + 2048>(vb); f.l1 = tr_read<base + 1 * 4096>(vb); f.h1 = tr_read<base + 1 * 4096 + 2048>(vb);
;   f.l2 = tr_read<base + 2 * 4096>(vb); f.h2 = tr_read<base + 2 * 4096 + 2048>(vb); f.l3 = tr_read<base + 3 * 4096>(vb); f.h3 = tr_read<base + 3 * 4096 + 2048>(vb);
; }
; __device__ __forceinline__ void pv_mma(f32x16& od, const VFrag& f, bf16x8 pa0, bf16x8 pa1, bf16x8 pa2, bf16x8 pa3) {
;     ...
;   od = __builtin_amdgcn_mfma_f32_32x32x16_bf16(pa0, PKV(f.l0, f.h0), od, 0, 0, 0);
;   od = __builtin_amdgcn_mfma_f32_32x32x16_bf16(pa1, PKV(f.l1, f.h1), od, 0, 0, 0);
;   od = __builtin_amdgcn_mfma_f32_32x32x16_bf16(pa2, PKV(f.l2, f.h2), od, 0, 0, 0);
;   od = __builtin_amdgcn_mfma_f32_32x32x16_bf16(pa3, PKV(f.l3, f.h3), od, 0, 0, 0);
;     ...
; }
; __device__ __forceinline__ void pv_all(f32x16* o, int vb, bf16x8 pa0, bf16x8 pa1, bf16x8 pa2, bf16x8 pa3) {
;   VFrag fc, fn;
;   pv_reads<0>(fc, vb);
;   PV_STEP(0); PV_STEP(1); PV_STEP(2); PV_STEP(3); PV_STEP(4); PV_STEP(5); PV_STEP(6);
;   asm volatile("s_waitcnt lgkmcnt(0)" ::: "memory"); SBAR(); pv_mma(o[7], fc, pa0, pa1, pa2, pa3);
; }
; __device__ __forceinline__ void attn_body256(const bf16_t* __restrict__ Qb, const bf16_t* __restrict__ Kh, const bf16_t* __restrict__ Vh,
;                                              bf16_t* Ob, int seq, unsigned char* lds, float lam, int MODE, bf16_t* Ab, const float* wsub) {
;     ...
;     pv_all(o, vb0 + b * A2_VBUF, pa0, pa1, pa2, pa3);
;     asm volatile("s_waitcnt vmcnt(0)" ::: "memory"); __syncthreads();
;     if (j + 2 < NT) A2_DMA(j + 2, b);
	v_mfma_f32_16x16x32_bf16 v[114:117], v[194:197], v[130:133], v[114:117]
	v_mfma_f32_16x16x32_bf16 v[118:121], v[194:197], v[134:137], v[118:121]
	v_mfma_f32_16x16x32_bf16 v[114:117], v[198:201], v[138:141], v[114:117]
	v_mfma_f32_16x16x32_bf16 v[118:121], v[198:201], v[142:145], v[118:121]
	ds_read_b64_tr_b16 v[194:195], v244 offset:1280
	ds_read_b64_tr_b16 v[196:197], v244 offset:5376
	ds_read_b64_tr_b16 v[198:199], v244 offset:9472
	ds_read_b64_tr_b16 v[200:201], v244 offset:13568
	s_waitcnt lgkmcnt(8)
	v_mfma_f32_16x16x32_bf16 v[122:125], v[146:149], v[130:133], v[122:125]
	v_mfma_f32_16x16x32_bf16 v[126:129], v[146:149], v[134:137], v[126:129]
	v_mfma_f32_16x16x32_bf16 v[122:125], v[150:153], v[138:141], v[122:125]
	v_mfma_f32_16x16x32_bf16 v[126:129], v[150:153], v[142:145], v[126:129]
	ds_read_b64_tr_b16 v[146:147], v244 offset:1536
	ds_read_b64_tr_b16 v[148:149], v244 offset:5632
	ds_read_b64_tr_b16 v[150:151], v244 offset:9728
	ds_read_b64_tr_b16 v[152:153], v244 offset:13824
	s_waitcnt lgkmcnt(8)
	v_mfma_f32_16x16x32_bf16 v[98:101], v[154:157], v[130:133], v[98:101]
	v_mfma_f32_16x16x32_bf16 v[102:105], v[154:157], v[134:137], v[102:105]
	v_mfma_f32_16x16x32_bf16 v[98:101], v[158:161], v[138:141], v[98:101]
	v_mfma_f32_16x16x32_bf16 v[102:105], v[158:161], v[142:145], v[102:105]
	ds_read_b64_tr_b16 v[154:155], v244 offset:1792
	ds_read_b64_tr_b16 v[156:157], v244 offset:5888
	ds_read_b64_tr_b16 v[158:159], v244 offset:9984
	ds_read_b64_tr_b16 v[160:161], v244 offset:14080
	s_waitcnt lgkmcnt(8)
	v_mfma_f32_16x16x32_bf16 v[106:109], v[194:197], v[130:133], v[106:109]
	v_mfma_f32_16x16x32_bf16 v[110:113], v[194:197], v[134:137], v[110:113]
	v_mfma_f32_16x16x32_bf16 v[106:109], v[198:201], v[138:141], v[106:109]
	v_mfma_f32_16x16x32_bf16 v[110:113], v[198:201], v[142:145], v[110:113]
	ds_read_b64_tr_b16 v[194:195], v244 offset:16384
	ds_read_b64_tr_b16 v[196:197], v244 offset:20480
	ds_read_b64_tr_b16 v[198:199], v244 offset:24576
	ds_read_b64_tr_b16 v[200:201], v244 offset:28672
	s_waitcnt lgkmcnt(8)
	v_mfma_f32_16x16x32_bf16 v[82:85], v[146:149], v[130:133], v[82:85]
	v_mfma_f32_16x16x32_bf16 v[86:89], v[146:149], v[134:137], v[86:89]
	v_mfma_f32_16x16x32_bf16 v[82:85], v[150:153], v[138:141], v[82:85]
	v_mfma_f32_16x16x32_bf16 v[86:89], v[150:153], v[142:145], v[86:89]
	ds_read_b64_tr_b16 v[146:147], v244 offset:16640
	ds_read_b64_tr_b16 v[148:149], v244 offset:20736
	ds_read_b64_tr_b16 v[150:151], v244 offset:24832
	ds_read_b64_tr_b16 v[152:153], v244 offset:28928
	s_waitcnt lgkmcnt(8)
	v_mfma_f32_16x16x32_bf16 v[90:93], v[154:157], v[130:133], v[90:93]
	v_mfma_f32_16x16x32_bf16 v[94:97], v[154:157], v[134:137], v[94:97]
	v_mfma_f32_16x16x32_bf16 v[90:93], v[158:161], v[138:141], v[90:93]
	v_mfma_f32_16x16x32_bf16 v[94:97], v[158:161], v[142:145], v[94:97]
	ds_read_b64_tr_b16 v[154:155], v244 offset:16896
	ds_read_b64_tr_b16 v[156:157], v244 offset:20992
	ds_read_b64_tr_b16 v[158:159], v244 offset:25088
	ds_read_b64_tr_b16 v[160:161], v244 offset:29184
	s_waitcnt lgkmcnt(8)
	v_mfma_f32_16x16x32_bf16 v[66:69], v[194:197], v[130:133], v[66:69]
	v_mfma_f32_16x16x32_bf16 v[70:73], v[194:197], v[134:137], v[70:73]
	v_mfma_f32_16x16x32_bf16 v[66:69], v[198:201], v[138:141], v[66:69]
	v_mfma_f32_16x16x32_bf16 v[70:73], v[198:201], v[142:145], v[70:73]
	ds_read_b64_tr_b16 v[194:195], v244 offset:17152
	ds_read_b64_tr_b16 v[196:197], v244 offset:21248
	ds_read_b64_tr_b16 v[198:199], v244 offset:25344
	ds_read_b64_tr_b16 v[200:201], v244 offset:29440
	s_waitcnt lgkmcnt(8)
	v_mfma_f32_16x16x32_bf16 v[74:77], v[146:149], v[130:133], v[74:77]
	v_mfma_f32_16x16x32_bf16 v[78:81], v[146:149], v[134:137], v[78:81]
	v_mfma_f32_16x16x32_bf16 v[74:77], v[150:153], v[138:141], v[74:77]
	v_mfma_f32_16x16x32_bf16 v[78:81], v[150:153], v[142:145], v[78:81]
	ds_read_b64_tr_b16 v[146:147], v244 offset:17408
	ds_read_b64_tr_b16 v[148:149], v244 offset:21504
	ds_read_b64_tr_b16 v[150:151], v244 offset:25600
	ds_read_b64_tr_b16 v[152:153], v244 offset:29696
	s_waitcnt lgkmcnt(8)
	v_mfma_f32_16x16x32_bf16 v[50:53], v[154:157], v[130:133], v[50:53]
	v_mfma_f32_16x16x32_bf16 v[54:57], v[154:157], v[134:137], v[54:57]
	v_mfma_f32_16x16x32_bf16 v[50:53], v[158:161], v[138:141], v[50:53]
	v_mfma_f32_16x16x32_bf16 v[54:57], v[158:161], v[142:145], v[54:57]
	ds_read_b64_tr_b16 v[154:155], v244 offset:17664
	ds_read_b64_tr_b16 v[156:157], v244 offset:21760
	ds_read_b64_tr_b16 v[158:159], v244 offset:25856
	ds_read_b64_tr_b16 v[160:161], v244 offset:29952
	s_waitcnt lgkmcnt(8)
	v_mfma_f32_16x16x32_bf16 v[58:61], v[194:197], v[130:133], v[58:61]
	v_mfma_f32_16x16x32_bf16 v[62:65], v[194:197], v[134:137], v[62:65]
	v_mfma_f32_16x16x32_bf16 v[58:61], v[198:201], v[138:141], v[58:61]
	v_mfma_f32_16x16x32_bf16 v[62:65], v[198:201], v[142:145], v[62:65]
	ds_read_b64_tr_b16 v[194:195], v244 offset:17920
	ds_read_b64_tr_b16 v[196:197], v244 offset:22016
	ds_read_b64_tr_b16 v[198:199], v244 offset:26112
	ds_read_b64_tr_b16 v[200:201], v244 offset:30208
	s_waitcnt lgkmcnt(8)
	v_mfma_f32_16x16x32_bf16 v[34:37], v[146:149], v[130:133], v[34:37]
	v_mfma_f32_16x16x32_bf16 v[38:41], v[146:149], v[134:137], v[38:41]
	v_mfma_f32_16x16x32_bf16 v[34:37], v[150:153], v[138:141], v[34:37]
	v_mfma_f32_16x16x32_bf16 v[38:41], v[150:153], v[142:145], v[38:41]
	ds_read_b64_tr_b16 v[146:147], v244 offset:18176
	ds_read_b64_tr_b16 v[148:149], v244 offset:22272
	ds_read_b64_tr_b16 v[150:151], v244 offset:26368
	ds_read_b64_tr_b16 v[152:153], v244 offset:30464
	s_waitcnt lgkmcnt(8)
	v_mfma_f32_16x16x32_bf16 v[42:45], v[154:157], v[130:133], v[42:45]
	v_mfma_f32_16x16x32_bf16 v[46:49], v[154:157], v[134:137], v[46:49]
	v_mfma_f32_16x16x32_bf16 v[42:45], v[158:161], v[138:141], v[42:45]
	v_mfma_f32_16x16x32_bf16 v[46:49], v[158:161], v[142:145], v[46:49]
	s_waitcnt lgkmcnt(4)
	v_mfma_f32_16x16x32_bf16 v[18:21], v[194:197], v[130:133], v[18:21]
	v_mfma_f32_16x16x32_bf16 v[22:25], v[194:197], v[134:137], v[22:25]
	v_mfma_f32_16x16x32_bf16 v[18:21], v[198:201], v[138:141], v[18:21]
	v_mfma_f32_16x16x32_bf16 v[22:25], v[198:201], v[142:145], v[22:25]
	s_waitcnt lgkmcnt(0)
	v_mfma_f32_16x16x32_bf16 v[26:29], v[146:149], v[130:133], v[26:29]
	v_mfma_f32_16x16x32_bf16 v[30:33], v[146:149], v[134:137], v[30:33]
	v_mfma_f32_16x16x32_bf16 v[26:29], v[150:153], v[138:141], v[26:29]
	v_mfma_f32_16x16x32_bf16 v[30:33], v[150:153], v[142:145], v[30:33]
	s_waitcnt vmcnt(0)
	s_barrier
; #define SBAR() __builtin_amdgcn_sched_barrier(0)
; __device__ __forceinline__ int crow(int r, int hi) { return (r & 3) + 8 * (r >> 2) + 4 * hi; }
; __device__ __forceinline__ int crow(int r, int hi) { return (r & 3) + 8 * (r >> 2) + 4 * hi; }
; __device__ __forceinline__ void attn_body256(const bf16_t* __restrict__ Qb, const bf16_t* __restrict__ Kh, const bf16_t* __restrict__ Vh,
;                                              bf16_t* Ob, int seq, unsigned char* lds, float lam, int MODE, bf16_t* Ab, const float* wsub) {
;     ...
;   for (int j = 0; j < NT; ++j) {
;     const int b = j & 1;
;     f32x16 p0, p1; float mn, alpha; bf16x8 pa0, pa1, pa2, pa3;
;     SBAR(); qkt(p0, p1, (const bf16_t*)(lds + A2_KOFF + b * A2_KBUF), qr, r32, hi);
;     partialSM(p0, p1, m_reg, mn, alpha);
;     if (__any(alpha < 1.f)) { if (hi == 0) al_l[r32] = alpha; asm volatile("s_waitcnt lgkmcnt(0)" ::: "memory");
; #pragma unroll
;       for (int r = 0; r < 16; ++r) { const float a = al_l[crow(r, hi)];
; #pragma unroll
;         for (int d = 0; d < 8; ++d) o[d][r] *= a; } }
;     finishSM(p0, p1, alpha, l_reg, pa0, pa1, pa2, pa3); SBAR();
;     pv_all(o, vb0 + b * A2_VBUF, pa0, pa1, pa2, pa3);
;     asm volatile("s_waitcnt vmcnt(0)" ::: "memory"); __syncthreads();
;     if (j + 2 < NT) A2_DMA(j + 2, b);
	s_xor_b32 s9, s25, 1
	s_lshl_b32 s9, s9, 14
	s_add_i32 s9, s9, 0x10000
	v_add_u32_e32 v230, s9, v232
	v_add_u32_e32 v247, s9, v233
	ds_read_b128 v[194:197], v230
	ds_read_b128 v[198:201], v230 offset:4096
	ds_read_b128 v[202:205], v230 offset:8192
	ds_read_b128 v[206:209], v230 offset:12288
	ds_read_b128 v[210:213], v247
	ds_read_b128 v[214:217], v247 offset:4096
	s_cmp_ge_u32 s13, s19
	s_cbranch_scc1 .Lat_x_nodma
	v_lshl_add_u64 v[130:131], v[220:221], 0, s[14:15]
	v_lshl_add_u64 v[132:133], v[222:223], 0, s[14:15]
	v_lshl_add_u64 v[134:135], v[224:225], 0, s[14:15]
	v_lshl_add_u64 v[136:137], v[226:227], 0, s[14:15]
	v_lshl_add_u64 v[138:139], v[134:135], 0, s[54:55]
	v_lshl_add_u64 v[134:135], v[134:135], 0, s[4:5]
	v_lshl_add_u64 v[140:141], v[136:137], 0, s[54:55]
	v_lshl_add_u64 v[136:137], v[136:137], 0, s[4:5]
	s_add_i32 s9, s22, s24
	s_add_i32 s8, s21, s100
	s_mov_b32 m0, s9
	s_nop 0
	global_load_lds_dwordx4 v[130:131], off
	s_add_i32 m0, s9, 0x2000
	s_nop 0
	global_load_lds_dwordx4 v[132:133], off
	s_mov_b32 m0, s8
	s_nop 0
	global_load_lds_dwordx4 v[138:139], off
	s_add_i32 m0, s8, 0x4000
	s_nop 0
	global_load_lds_dwordx4 v[134:135], off
	s_add_i32 m0, s8, 0x2000
	s_nop 0
	global_load_lds_dwordx4 v[140:141], off
	s_add_i32 m0, s8, 0x6000
	s_nop 0
	global_load_lds_dwordx4 v[136:137], off
.Lat_x_nodma:
	s_mov_b32 s101, s98
	s_mov_b32 s98, s99
	s_mov_b32 s99, s100
	s_mov_b32 s100, s101
	s_add_u32 s14, s14, 0x40000
	s_addc_u32 s15, s15, 0
	s_add_i32 s13, s13, 1
	s_cmp_eq_u32 s23, s14
	s_cbranch_scc0 .Lat_x_top
	s_waitcnt lgkmcnt(0)
	s_branch .Lat_epi
.Lat_y_top:
	s_waitcnt lgkmcnt(8)
	v_mfma_f32_16x16x32_bf16 v[2:5], v[146:149], v[130:133], v[2:5]
	v_mfma_f32_16x16x32_bf16 v[6:9], v[146:149], v[134:137], v[6:9]
	v_mfma_f32_16x16x32_bf16 v[2:5], v[150:153], v[138:141], v[2:5]
	v_mfma_f32_16x16x32_bf16 v[6:9], v[150:153], v[142:145], v[6:9]
	ds_read_b64_tr_b16 v[146:147], v244 offset:768
	ds_read_b64_tr_b16 v[148:149], v244 offset:4864
	ds_read_b64_tr_b16 v[150:151], v244 offset:8960
	ds_read_b64_tr_b16 v[152:153], v244 offset:13056
	s_waitcnt lgkmcnt(8)
	v_mfma_f32_16x16x32_bf16 v[10:13], v[154:157], v[130:133], v[10:13]
	v_mfma_f32_16x16x32_bf16 v[14:17], v[154:157], v[134:137], v[14:17]
	v_mfma_f32_16x16x32_bf16 v[10:13], v[158:161], v[138:141], v[10:13]
	v_mfma_f32_16x16x32_bf16 v[14:17], v[158:161], v[142:145], v[14:17]
	ds_read_b64_tr_b16 v[154:155], v244 offset:1024
	ds_read_b64_tr_b16 v[156:157], v244 offset:5120
	ds_read_b64_tr_b16 v[158:159], v244 offset:9216
	ds_read_b64_tr_b16 v[160:161], v244 offset:13312
	s_waitcnt lgkmcnt(8)
	v_mfma_f32_16x16x32_bf16 v[114:117], v[194:197], v[130:133], v[114:117]
	v_mfma_f32_16x16x32_bf16 v[118:121], v[194:197], v[134:137], v[118:121]
	v_mfma_f32_16x16x32_bf16 v[114:117], v[198:201], v[138:141], v[114:117]
	v_mfma_f32_16x16x32_bf16 v[118:121], v[198:201], v[142:145], v[118:121]
	ds_read_b64_tr_b16 v[194:195], v244 offset:1280
	ds_read_b64_tr_b16 v[196:197], v244 offset:5376
	ds_read_b64_tr_b16 v[198:199], v244 offset:9472
	ds_read_b64_tr_b16 v[200:201], v244 offset:13568
	s_waitcnt lgkmcnt(8)
	v_mfma_f32_16x16x32_bf16 v[122:125], v[146:149], v[130:133], v[122:125]
	v_mfma_f32_16x16x32_bf16 v[126:129], v[146:149], v[134:137], v[126:129]
	v_mfma_f32_16x16x32_bf16 v[122:125], v[150:153], v[138:141], v[122:125]
	v_mfma_f32_16x16x32_bf16 v[126:129], v[150:153], v[142:145], v[126:129]
	ds_read_b64_tr_b16 v[146:147], v244 offset:1536
	ds_read_b64_tr_b16 v[148:149], v244 offset:5632
	ds_read_b64_tr_b16 v[150:151], v244 offset:9728
	ds_read_b64_tr_b16 v[152:153], v244 offset:13824
	s_waitcnt lgkmcnt(8)
	v_mfma_f32_16x16x32_bf16 v[98:101], v[154:157], v[130:133], v[98:101]
	v_mfma_f32_16x16x32_bf16 v[102:105], v[154:157], v[134:137], v[102:105]
	v_mfma_f32_16x16x32_bf16 v[98:101], v[158:161], v[138:141], v[98:101]
	v_mfma_f32_16x16x32_bf16 v[102:105], v[158:161], v[142:145], v[102:105]
	ds_read_b64_tr_b16 v[154:155], v244 offset:1792
	ds_read_b64_tr_b16 v[156:157], v244 offset:5888
	ds_read_b64_tr_b16 v[158:159], v244 offset:9984
	ds_read_b64_tr_b16 v[160:161], v244 offset:14080
	s_waitcnt lgkmcnt(8)
	v_mfma_f32_16x16x32_bf16 v[106:109], v[194:197], v[130:133], v[106:109]
	v_mfma_f32_16x16x32_bf16 v[110:113], v[194:197], v[134:137], v[110:113]
	v_mfma_f32_16x16x32_bf16 v[106:109], v[198:201], v[138:141], v[106:109]
	v_mfma_f32_16x16x32_bf16 v[110:113], v[198:201], v[142:145], v[110:113]
	ds_read_b64_tr_b16 v[194:195], v244 offset:16384
	ds_read_b64_tr_b16 v[196:197], v244 offset:20480
	ds_read_b64_tr_b16 v[198:199], v244 offset:24576
	ds_read_b64_tr_b16 v[200:201], v244 offset:28672
	s_waitcnt lgkmcnt(8)
	v_mfma_f32_16x16x32_bf16 v[82:85], v[146:149], v[130:133], v[82:85]
	v_mfma_f32_16x16x32_bf16 v[86:89], v[146:149], v[134:137], v[86:89]
	v_mfma_f32_16x16x32_bf16 v[82:85], v[150:153], v[138:141], v[82:85]
	v_mfma_f32_16x16x32_bf16 v[86:89], v[150:153], v[142:145], v[86:89]
	ds_read_b64_tr_b16 v[146:147], v244 offset:16640
	ds_read_b64_tr_b16 v[148:149], v244 offset:20736
	ds_read_b64_tr_b16 v[150:151], v244 offset:24832
	ds_read_b64_tr_b16 v[152:153], v244 offset:28928
	s_waitcnt lgkmcnt(8)
	v_mfma_f32_16x16x32_bf16 v[90:93], v[154:157], v[130:133], v[90:93]
	v_mfma_f32_16x16x32_bf16 v[94:97], v[154:157], v[134:137], v[94:97]
	v_mfma_f32_16x16x32_bf16 v[90:93], v[158:161], v[138:141], v[90:93]
	v_mfma_f32_16x16x32_bf16 v[94:97], v[158:161], v[142:145], v[94:97]
	ds_read_b64_tr_b16 v[154:155], v244 offset:16896
	ds_read_b64_tr_b16 v[156:157], v244 offset:20992
	ds_read_b64_tr_b16 v[158:159], v244 offset:25088
	ds_read_b64_tr_b16 v[160:161], v244 offset:29184
	s_waitcnt lgkmcnt(8)
; #define SBAR() __builtin_amdgcn_sched_barrier(0)
; #define PV_STEP(B) do { pv_reads<(B) + 1>(fn, vb); asm volatile("s_waitcnt lgkmcnt(8)" ::: "memory"); SBAR(); pv_mma(o[B], fc, pa0, pa1, pa2, pa3); SBAR(); fc = fn; } while (0)
; __device__ __forceinline__ void pv_mma(f32x16& od, const VFrag& f, bf16x8 pa0, bf16x8 pa1, bf16x8 pa2, bf16x8 pa3) {
;     ...
;   od = __builtin_amdgcn_mfma_f32_32x32x16_bf16(pa0, PKV(f.l0, f.h0), od, 0, 0, 0);
;   od = __builtin_amdgcn_mfma_f32_32x32x16_bf16(pa1, PKV(f.l1, f.h1), od, 0, 0, 0);
;   od = __builtin_amdgcn_mfma_f32_32x32x16_bf16(pa2, PKV(f.l2, f.h2), od, 0, 0, 0);
;   od = __builtin_amdgcn_mfma_f32_32x32x16_bf16(pa3, PKV(f.l3, f.h3), od, 0, 0, 0);
;     ...
; }
; __device__ __forceinline__ void pv_all(f32x16* o, int vb, bf16x8 pa0, bf16x8 pa1, bf16x8 pa2, bf16x8 pa3) {
;   VFrag fc, fn;
;   pv_reads<0>(fc, vb);
;   PV_STEP(0); PV_STEP(1); PV_STEP(2); PV_STEP(3); PV_STEP(4); PV_STEP(5); PV_STEP(6);
;   asm volatile("s_waitcnt lgkmcnt(0)" ::: "memory"); SBAR(); pv_mma(o[7], fc, pa0, pa1, pa2, pa3);
; }
	v_mfma_f32_16x16x32_bf16 v[66:69], v[194:197], v[130:133], v[66:69]
	v_mfma_f32_16x16x32_bf16 v[70:73], v[194:197], v[134:137], v[70:73]
	v_mfma_f32_16x16x32_bf16 v[66:69], v[198:201], v[138:141], v[66:69]
	v_mfma_f32_16x16x32_bf16 v[70:73], v[198:201], v[142:145], v[70:73]
	ds_read_b64_tr_b16 v[194:195], v244 offset:17152
	ds_read_b64_tr_b16 v[196:197], v244 offset:21248
	ds_read_b64_tr_b16 v[198:199], v244 offset:25344
	ds_read_b64_tr_b16 v[200:201], v244 offset:29440
	s_waitcnt lgkmcnt(8)
	v_mfma_f32_16x16x32_bf16 v[74:77], v[146:149], v[130:133], v[74:77]
	v_mfma_f32_16x16x32_bf16 v[78:81], v[146:149], v[134:137], v[78:81]
	v_mfma_f32_16x16x32_bf16 v[74:77], v[150:153], v[138:141], v[74:77]
	v_mfma_f32_16x16x32_bf16 v[78:81], v[150:153], v[142:145], v[78:81]
	ds_read_b64_tr_b16 v[146:147], v244 offset:17408
	ds_read_b64_tr_b16 v[148:149], v244 offset:21504
	ds_read_b64_tr_b16 v[150:151], v244 offset:25600
	ds_read_b64_tr_b16 v[152:153], v244 offset:29696
	s_waitcnt lgkmcnt(8)
	v_mfma_f32_16x16x32_bf16 v[50:53], v[154:157], v[130:133], v[50:53]
	v_mfma_f32_16x16x32_bf16 v[54:57], v[154:157], v[134:137], v[54:57]
	v_mfma_f32_16x16x32_bf16 v[50:53], v[158:161], v[138:141], v[50:53]
	v_mfma_f32_16x16x32_bf16 v[54:57], v[158:161], v[142:145], v[54:57]
	ds_read_b64_tr_b16 v[154:155], v244 offset:17664
	ds_read_b64_tr_b16 v[156:157], v244 offset:21760
	ds_read_b64_tr_b16 v[158:159], v244 offset:25856
	ds_read_b64_tr_b16 v[160:161], v244 offset:29952
	s_waitcnt lgkmcnt(8)
	v_mfma_f32_16x16x32_bf16 v[58:61], v[194:197], v[130:133], v[58:61]
	v_mfma_f32_16x16x32_bf16 v[62:65], v[194:197], v[134:137], v[62:65]
	v_mfma_f32_16x16x32_bf16 v[58:61], v[198:201], v[138:141], v[58:61]
	v_mfma_f32_16x16x32_bf16 v[62:65], v[198:201], v[142:145], v[62:65]
	ds_read_b64_tr_b16 v[194:195], v244 offset:17920
	ds_read_b64_tr_b16 v[196:197], v244 offset:22016
	ds_read_b64_tr_b16 v[198:199], v244 offset:26112
	ds_read_b64_tr_b16 v[200:201], v244 offset:30208
	s_waitcnt lgkmcnt(8)
	v_mfma_f32_16x16x32_bf16 v[34:37], v[146:149], v[130:133], v[34:37]
	v_mfma_f32_16x16x32_bf16 v[38:41], v[146:149], v[134:137], v[38:41]
	v_mfma_f32_16x16x32_bf16 v[34:37], v[150:153], v[138:141], v[34:37]
	v_mfma_f32_16x16x32_bf16 v[38:41], v[150:153], v[142:145], v[38:41]
	ds_read_b64_tr_b16 v[146:147], v244 offset:18176
	ds_read_b64_tr_b16 v[148:149], v244 offset:22272
	ds_read_b64_tr_b16 v[150:151], v244 offset:26368
	ds_read_b64_tr_b16 v[152:153], v244 offset:30464
	s_waitcnt lgkmcnt(8)
	v_mfma_f32_16x16x32_bf16 v[42:45], v[154:157], v[130:133], v[42:45]
	v_mfma_f32_16x16x32_bf16 v[46:49], v[154:157], v[134:137], v[46:49]
	v_mfma_f32_16x16x32_bf16 v[42:45], v[158:161], v[138:141], v[42:45]
	v_mfma_f32_16x16x32_bf16 v[46:49], v[158:161], v[142:145], v[46:49]
	s_waitcnt lgkmcnt(4)
	v_mfma_f32_16x16x32_bf16 v[18:21], v[194:197], v[130:133], v[18:21]
	v_mfma_f32_16x16x32_bf16 v[22:25], v[194:197], v[134:137], v[22:25]
	v_mfma_f32_16x16x32_bf16 v[18:21], v[198:201], v[138:141], v[18:21]
	v_mfma_f32_16x16x32_bf16 v[22:25], v[198:201], v[142:145], v[22:25]
	s_waitcnt lgkmcnt(0)
	v_mfma_f32_16x16x32_bf16 v[26:29], v[146:149], v[130:133], v[26:29]
	v_mfma_f32_16x16x32_bf16 v[30:33], v[146:149], v[134:137], v[30:33]
	v_mfma_f32_16x16x32_bf16 v[26:29], v[150:153], v[138:141], v[26:29]
	v_mfma_f32_16x16x32_bf16 v[30:33], v[150:153], v[142:145], v[30:33]
	s_cmp_gt_u32 s13, s19
	s_cbranch_scc1 .Lat_y_nodma
	s_sub_u32 s16, s14, 0x40000
	s_subb_u32 s17, s15, 0
	v_lshl_add_u64 v[130:131], v[220:221], 0, s[16:17]
	v_lshl_add_u64 v[132:133], v[222:223], 0, s[16:17]
	v_lshl_add_u64 v[134:135], v[224:225], 0, s[16:17]
	v_lshl_add_u64 v[136:137], v[226:227], 0, s[16:17]
	v_lshl_add_u64 v[138:139], v[134:135], 0, s[54:55]
	v_lshl_add_u64 v[134:135], v[134:135], 0, s[4:5]
	v_lshl_add_u64 v[140:141], v[136:137], 0, s[54:55]
	v_lshl_add_u64 v[136:137], v[136:137], 0, s[4:5]
	s_add_i32 s9, s22, s24
	s_add_i32 s8, s21, s99
	s_mov_b32 m0, s9
	s_nop 0
	global_load_lds_dwordx4 v[130:131], off
	s_add_i32 m0, s9, 0x2000
	s_nop 0
	global_load_lds_dwordx4 v[132:133], off
	s_mov_b32 m0, s8
	s_nop 0
	global_load_lds_dwordx4 v[138:139], off
	s_add_i32 m0, s8, 0x4000
	s_nop 0
	global_load_lds_dwordx4 v[134:135], off
	s_add_i32 m0, s8, 0x2000
	s_nop 0
	global_load_lds_dwordx4 v[140:141], off
	s_add_i32 m0, s8, 0x6000
	s_nop 0
	global_load_lds_dwordx4 v[136:137], off
; __device__ __forceinline__ void partialSM(f32x16& p0, f32x16& p1, float& m_reg, float& mn, float& alpha) {
;   constexpr float C = SCALE * 1.4426950408889634f;
;   float pmax = p0[0]; for (int r = 1; r < 16; ++r) pmax = fmaxf(pmax, p0[r]); for (int r = 0; r < 16; ++r) pmax = fmaxf(pmax, p1[r]);
;   { auto rr = __builtin_amdgcn_permlane32_swap(__float_as_uint(pmax), __float_as_uint(pmax), false, false);
;     pmax = fmaxf(__uint_as_float(rr[0]), __uint_as_float(rr[1])); }
;   if (__builtin_expect(__all(pmax - m_reg <= THR / SCALE), 1)) { mn = m_reg; alpha = 1.f; }
;   else { mn = fmaxf(m_reg, pmax); alpha = __builtin_amdgcn_exp2f((m_reg - mn) * C); m_reg = mn; }
;   float mnC = -mn * C;
;   for (int r = 0; r < 16; ++r) p0[r] = fmaf(p0[r], C, mnC); for (int r = 0; r < 16; ++r) p1[r] = fmaf(p1[r], C, mnC);
;   for (int r = 0; r < 16; ++r) p0[r] = __builtin_amdgcn_exp2f(p0[r]);
; }
; __device__ __forceinline__ void qkt(f32x16& p0, f32x16& p1, const bf16_t* Ks, const bf16x8* qr, int r32, int hi) {
;   p0 = f32x16{}; p1 = f32x16{};
;   for (int d0 = 0; d0 < 8; ++d0) { int cb = (d0 * 16 + hi * 8) * 2;
;     bf16x8 b0 = *reinterpret_cast<const bf16x8*>((const char*)Ks + KSWZ(r32, cb));
;     bf16x8 b1 = *reinterpret_cast<const bf16x8*>((const char*)Ks + KSWZ(32 + r32, cb));
;     p0 = __builtin_amdgcn_mfma_f32_32x32x16_bf16(b0, qr[d0], p0, 0, 0, 0);
;     p1 = __builtin_amdgcn_mfma_f32_32x32x16_bf16(b1, qr[d0], p1, 0, 0, 0); }
; }
.Lat_y_nodma:
.Lat_y_qk:
	s_add_i32 s8, s13, -2
	s_and_b32 s25, s8, 1
	s_lshl_b32 s24, s25, 14
	s_add_i32 s8, s24, 0x10000
	v_add_u32_e32 v230, s8, v232
	v_add_u32_e32 v247, s8, v233
	s_setprio 1
	ds_read_b128 v[194:197], v230
	ds_read_b128 v[198:201], v230 offset:4096
	ds_read_b128 v[202:205], v230 offset:8192
	ds_read_b128 v[206:209], v230 offset:12288
	ds_read_b128 v[210:213], v247
	ds_read_b128 v[214:217], v247 offset:4096
	s_waitcnt lgkmcnt(5)
	v_mfma_f32_16x16x32_bf16 v[130:133], v[194:197], v[162:165], 0
	v_mfma_f32_16x16x32_bf16 v[134:137], v[194:197], v[178:181], 0
	ds_read_b128 v[194:197], v247 offset:8192
	s_waitcnt lgkmcnt(5)
	v_mfma_f32_16x16x32_bf16 v[138:141], v[198:201], v[162:165], 0
	v_mfma_f32_16x16x32_bf16 v[142:145], v[198:201], v[178:181], 0
	ds_read_b128 v[198:201], v247 offset:12288
	s_waitcnt lgkmcnt(5)
	v_mfma_f32_16x16x32_bf16 v[146:149], v[202:205], v[162:165], 0
	v_mfma_f32_16x16x32_bf16 v[150:153], v[202:205], v[178:181], 0
	ds_read_b128 v[202:205], v230 offset:128
	s_waitcnt lgkmcnt(5)
	v_mfma_f32_16x16x32_bf16 v[154:157], v[206:209], v[162:165], 0
	v_mfma_f32_16x16x32_bf16 v[158:161], v[206:209], v[178:181], 0
	ds_read_b128 v[206:209], v230 offset:4224
	s_waitcnt lgkmcnt(5)
	v_mfma_f32_16x16x32_bf16 v[130:133], v[210:213], v[166:169], v[130:133]
	v_mfma_f32_16x16x32_bf16 v[134:137], v[210:213], v[182:185], v[134:137]
	ds_read_b128 v[210:213], v230 offset:8320
	s_waitcnt lgkmcnt(5)
	v_mfma_f32_16x16x32_bf16 v[138:141], v[214:217], v[166:169], v[138:141]
	v_mfma_f32_16x16x32_bf16 v[142:145], v[214:217], v[182:185], v[142:145]
	ds_read_b128 v[214:217], v230 offset:12416
	s_waitcnt lgkmcnt(5)
	v_mfma_f32_16x16x32_bf16 v[146:149], v[194:197], v[166:169], v[146:149]
	v_mfma_f32_16x16x32_bf16 v[150:153], v[194:197], v[182:185], v[150:153]
	ds_read_b128 v[194:197], v247 offset:128
	s_waitcnt lgkmcnt(5)
	v_mfma_f32_16x16x32_bf16 v[154:157], v[198:201], v[166:169], v[154:157]
	v_mfma_f32_16x16x32_bf16 v[158:161], v[198:201], v[182:185], v[158:161]
	ds_read_b128 v[198:201], v247 offset:4224
	s_waitcnt lgkmcnt(5)
	v_mfma_f32_16x16x32_bf16 v[130:133], v[202:205], v[170:173], v[130:133]
	v_mfma_f32_16x16x32_bf16 v[134:137], v[202:205], v[186:189], v[134:137]
	ds_read_b128 v[202:205], v247 offset:8320
	s_waitcnt lgkmcnt(5)
	v_mfma_f32_16x16x32_bf16 v[138:141], v[206:209], v[170:173], v[138:141]
	v_mfma_f32_16x16x32_bf16 v[142:145], v[206:209], v[186:189], v[142:145]
	ds_read_b128 v[206:209], v247 offset:12416
	s_waitcnt lgkmcnt(5)
	v_mfma_f32_16x16x32_bf16 v[146:149], v[210:213], v[170:173], v[146:149]
	v_mfma_f32_16x16x32_bf16 v[150:153], v[210:213], v[186:189], v[150:153]
	s_waitcnt lgkmcnt(4)
	v_mfma_f32_16x16x32_bf16 v[154:157], v[214:217], v[170:173], v[154:157]
	v_mfma_f32_16x16x32_bf16 v[158:161], v[214:217], v[186:189], v[158:161]
	s_waitcnt lgkmcnt(3)
	v_mfma_f32_16x16x32_bf16 v[130:133], v[194:197], v[174:177], v[130:133]
	v_mfma_f32_16x16x32_bf16 v[134:137], v[194:197], v[190:193], v[134:137]
	s_waitcnt lgkmcnt(2)
	v_mfma_f32_16x16x32_bf16 v[138:141], v[198:201], v[174:177], v[138:141]
	v_mfma_f32_16x16x32_bf16 v[142:145], v[198:201], v[190:193], v[142:145]
	s_waitcnt lgkmcnt(1)
	v_mfma_f32_16x16x32_bf16 v[146:149], v[202:205], v[174:177], v[146:149]
	v_mfma_f32_16x16x32_bf16 v[150:153], v[202:205], v[190:193], v[150:153]
	s_waitcnt lgkmcnt(0)
	v_mfma_f32_16x16x32_bf16 v[154:157], v[206:209], v[174:177], v[154:157]
	v_mfma_f32_16x16x32_bf16 v[158:161], v[206:209], v[190:193], v[158:161]
	s_setprio 0
	s_nop 6
	v_max3_f32 v194, v130, v131, v132
	v_max3_f32 v194, v194, v133, v138
	v_max3_f32 v194, v194, v139, v140
	v_max3_f32 v194, v194, v141, v146
	v_max3_f32 v194, v194, v147, v148
	v_max3_f32 v194, v194, v149, v154
	v_max3_f32 v194, v194, v155, v156
	v_max_f32_e32 v194, v194, v157
	v_max3_f32 v195, v134, v135, v136
	v_max3_f32 v195, v195, v137, v142
	v_max3_f32 v195, v195, v143, v144
	v_max3_f32 v195, v195, v145, v150
	v_max3_f32 v195, v195, v151, v152
	v_max3_f32 v195, v195, v153, v158
	v_max3_f32 v195, v195, v159, v160
	v_max_f32_e32 v195, v195, v161
	v_mov_b32_e32 v196, v194
	v_mov_b32_e32 v197, v195
	s_nop 1
	v_permlane32_swap_b32_e32 v194, v196
	v_permlane32_swap_b32_e32 v195, v197
	v_max_f32_e32 v194, v194, v196
	v_max_f32_e32 v195, v195, v197
	v_mov_b32_e32 v196, v194
	v_mov_b32_e32 v197, v195
	s_nop 1
	v_permlane16_swap_b32_e32 v194, v196
	v_permlane16_swap_b32_e32 v195, v197
	v_max_f32_e32 v194, v194, v196
	v_max_f32_e32 v195, v195, v197
	v_sub_f32_e32 v196, v194, v249
	v_sub_f32_e32 v197, v195, v246
	v_max_f32_e32 v196, v196, v197
	v_cmp_ge_f32_e32 vcc, 0x42b504f3, v196
	v_max_f32_e32 v198, v249, v194
	v_max_f32_e32 v199, v246, v195
	v_sub_f32_e32 v196, v249, v198
	v_sub_f32_e32 v197, v246, v199
	v_mul_f32_e32 v196, 0x3e0293ee, v196
	v_mul_f32_e32 v197, 0x3e0293ee, v197
	v_exp_f32_e32 v196, v196
	v_exp_f32_e32 v197, v197
	s_cmp_eq_u64 vcc, exec
	s_cselect_b64 s[8:9], -1, 0
	v_cndmask_b32_e64 v236, v196, 1.0, s[8:9]
	v_cndmask_b32_e64 v240, v197, 1.0, s[8:9]
	v_cndmask_b32_e64 v249, v198, v249, s[8:9]
	v_cndmask_b32_e64 v246, v199, v246, s[8:9]
	s_cbranch_scc1 .Lat_y_noresc
; __device__ __forceinline__ int crow(int r, int hi) { return (r & 3) + 8 * (r >> 2) + 4 * hi; }
; __device__ __forceinline__ int crow(int r, int hi) { return (r & 3) + 8 * (r >> 2) + 4 * hi; }
; __device__ __forceinline__ void partialSM(f32x16& p0, f32x16& p1, float& m_reg, float& mn, float& alpha) {
;     ...
;   if (__builtin_expect(__all(pmax - m_reg <= THR / SCALE), 1)) { mn = m_reg; alpha = 1.f; }
;   else { mn = fmaxf(m_reg, pmax); alpha = __builtin_amdgcn_exp2f((m_reg - mn) * C); m_reg = mn; }
;   float mnC = -mn * C;
;   for (int r = 0; r < 16; ++r) p0[r] = fmaf(p0[r], C, mnC); for (int r = 0; r < 16; ++r) p1[r] = fmaf(p1[r], C, mnC);
;   for (int r = 0; r < 16; ++r) p0[r] = __builtin_amdgcn_exp2f(p0[r]);
; __device__ __forceinline__ void attn_body256(const bf16_t* __restrict__ Qb, const bf16_t* __restrict__ Kh, const bf16_t* __restrict__ Vh,
;                                              bf16_t* Ob, int seq, unsigned char* lds, float lam, int MODE, bf16_t* Ab, const float* wsub) {
;     ...
;     if (__any(alpha < 1.f)) { if (hi == 0) al_l[r32] = alpha; asm volatile("s_waitcnt lgkmcnt(0)" ::: "memory");
; #pragma unroll
;       for (int r = 0; r < 16; ++r) { const float a = al_l[crow(r, hi)];
; #pragma unroll
;         for (int d = 0; d < 8; ++d) o[d][r] *= a; } }
	v_pk_mul_f32 v[2:3], v[2:3], v[236:237] op_sel_hi:[1,0]
	v_pk_mul_f32 v[4:5], v[4:5], v[236:237] op_sel_hi:[1,0]
	v_pk_mul_f32 v[6:7], v[6:7], v[240:241] op_sel_hi:[1,0]
	v_pk_mul_f32 v[8:9], v[8:9], v[240:241] op_sel_hi:[1,0]
	v_pk_mul_f32 v[10:11], v[10:11], v[236:237] op_sel_hi:[1,0]
	v_pk_mul_f32 v[12:13], v[12:13], v[236:237] op_sel_hi:[1,0]
	v_pk_mul_f32 v[14:15], v[14:15], v[240:241] op_sel_hi:[1,0]
	v_pk_mul_f32 v[16:17], v[16:17], v[240:241] op_sel_hi:[1,0]
	v_pk_mul_f32 v[114:115], v[114:115], v[236:237] op_sel_hi:[1,0]
	v_pk_mul_f32 v[116:117], v[116:117], v[236:237] op_sel_hi:[1,0]
	v_pk_mul_f32 v[118:119], v[118:119], v[240:241] op_sel_hi:[1,0]
	v_pk_mul_f32 v[120:121], v[120:121], v[240:241] op_sel_hi:[1,0]
	v_pk_mul_f32 v[122:123], v[122:123], v[236:237] op_sel_hi:[1,0]
	v_pk_mul_f32 v[124:125], v[124:125], v[236:237] op_sel_hi:[1,0]
	v_pk_mul_f32 v[126:127], v[126:127], v[240:241] op_sel_hi:[1,0]
	v_pk_mul_f32 v[128:129], v[128:129], v[240:241] op_sel_hi:[1,0]
	v_pk_mul_f32 v[98:99], v[98:99], v[236:237] op_sel_hi:[1,0]
	v_pk_mul_f32 v[100:101], v[100:101], v[236:237] op_sel_hi:[1,0]
	v_pk_mul_f32 v[102:103], v[102:103], v[240:241] op_sel_hi:[1,0]
	v_pk_mul_f32 v[104:105], v[104:105], v[240:241] op_sel_hi:[1,0]
	v_pk_mul_f32 v[106:107], v[106:107], v[236:237] op_sel_hi:[1,0]
	v_pk_mul_f32 v[108:109], v[108:109], v[236:237] op_sel_hi:[1,0]
	v_pk_mul_f32 v[110:111], v[110:111], v[240:241] op_sel_hi:[1,0]
	v_pk_mul_f32 v[112:113], v[112:113], v[240:241] op_sel_hi:[1,0]
	v_pk_mul_f32 v[82:83], v[82:83], v[236:237] op_sel_hi:[1,0]
	v_pk_mul_f32 v[84:85], v[84:85], v[236:237] op_sel_hi:[1,0]
	v_pk_mul_f32 v[86:87], v[86:87], v[240:241] op_sel_hi:[1,0]
	v_pk_mul_f32 v[88:89], v[88:89], v[240:241] op_sel_hi:[1,0]
	v_pk_mul_f32 v[90:91], v[90:91], v[236:237] op_sel_hi:[1,0]
	v_pk_mul_f32 v[92:93], v[92:93], v[236:237] op_sel_hi:[1,0]
	v_pk_mul_f32 v[94:95], v[94:95], v[240:241] op_sel_hi:[1,0]
	v_pk_mul_f32 v[96:97], v[96:97], v[240:241] op_sel_hi:[1,0]
	v_pk_mul_f32 v[66:67], v[66:67], v[236:237] op_sel_hi:[1,0]
	v_pk_mul_f32 v[68:69], v[68:69], v[236:237] op_sel_hi:[1,0]
	v_pk_mul_f32 v[70:71], v[70:71], v[240:241] op_sel_hi:[1,0]
	v_pk_mul_f32 v[72:73], v[72:73], v[240:241] op_sel_hi:[1,0]
	v_pk_mul_f32 v[74:75], v[74:75], v[236:237] op_sel_hi:[1,0]
	v_pk_mul_f32 v[76:77], v[76:77], v[236:237] op_sel_hi:[1,0]
	v_pk_mul_f32 v[78:79], v[78:79], v[240:241] op_sel_hi:[1,0]
	v_pk_mul_f32 v[80:81], v[80:81], v[240:241] op_sel_hi:[1,0]
	v_pk_mul_f32 v[50:51], v[50:51], v[236:237] op_sel_hi:[1,0]
	v_pk_mul_f32 v[52:53], v[52:53], v[236:237] op_sel_hi:[1,0]
	v_pk_mul_f32 v[54:55], v[54:55], v[240:241] op_sel_hi:[1,0]
	v_pk_mul_f32 v[56:57], v[56:57], v[240:241] op_sel_hi:[1,0]
	v_pk_mul_f32 v[58:59], v[58:59], v[236:237] op_sel_hi:[1,0]
	v_pk_mul_f32 v[60:61], v[60:61], v[236:237] op_sel_hi:[1,0]
	v_pk_mul_f32 v[62:63], v[62:63], v[240:241] op_sel_hi:[1,0]
	v_pk_mul_f32 v[64:65], v[64:65], v[240:241] op_sel_hi:[1,0]
	v_pk_mul_f32 v[34:35], v[34:35], v[236:237] op_sel_hi:[1,0]
	v_pk_mul_f32 v[36:37], v[36:37], v[236:237] op_sel_hi:[1,0]
	v_pk_mul_f32 v[38:39], v[38:39], v[240:241] op_sel_hi:[1,0]
	v_pk_mul_f32 v[40:41], v[40:41], v[240:241] op_sel_hi:[1,0]
	v_pk_mul_f32 v[42:43], v[42:43], v[236:237] op_sel_hi:[1,0]
	v_pk_mul_f32 v[44:45], v[44:45], v[236:237] op_sel_hi:[1,0]
	v_pk_mul_f32 v[46:47], v[46:47], v[240:241] op_sel_hi:[1,0]
	v_pk_mul_f32 v[48:49], v[48:49], v[240:241] op_sel_hi:[1,0]
	v_pk_mul_f32 v[18:19], v[18:19], v[236:237] op_sel_hi:[1,0]
	v_pk_mul_f32 v[20:21], v[20:21], v[236:237] op_sel_hi:[1,0]
	v_pk_mul_f32 v[22:23], v[22:23], v[240:241] op_sel_hi:[1,0]
	v_pk_mul_f32 v[24:25], v[24:25], v[240:241] op_sel_hi:[1,0]
	v_pk_mul_f32 v[26:27], v[26:27], v[236:237] op_sel_hi:[1,0]
	v_pk_mul_f32 v[28:29], v[28:29], v[236:237] op_sel_hi:[1,0]
	v_pk_mul_f32 v[30:31], v[30:31], v[240:241] op_sel_hi:[1,0]
	v_pk_mul_f32 v[32:33], v[32:33], v[240:241] op_sel_hi:[1,0]
.Lat_y_noresc:
	v_mul_f32_e32 v198, 0xbe0293ee, v249
	v_mul_f32_e32 v199, 0xbe0293ee, v246
	v_fmamk_f32 v130, v130, 0x3e0293ee, v198
	v_fmamk_f32 v131, v131, 0x3e0293ee, v198
	v_fmamk_f32 v132, v132, 0x3e0293ee, v198
	v_fmamk_f32 v133, v133, 0x3e0293ee, v198
	v_fmamk_f32 v134, v134, 0x3e0293ee, v199
	v_fmamk_f32 v135, v135, 0x3e0293ee, v199
	v_fmamk_f32 v136, v136, 0x3e0293ee, v199
	v_fmamk_f32 v137, v137, 0x3e0293ee, v199
	v_fmamk_f32 v138, v138, 0x3e0293ee, v198
	v_fmamk_f32 v139, v139, 0x3e0293ee, v198
	v_fmamk_f32 v140, v140, 0x3e0293ee, v198
	v_fmamk_f32 v141, v141, 0x3e0293ee, v198
	v_fmamk_f32 v142, v142, 0x3e0293ee, v199
	v_fmamk_f32 v143, v143, 0x3e0293ee, v199
	v_fmamk_f32 v144, v144, 0x3e0293ee, v199
	v_fmamk_f32 v145, v145, 0x3e0293ee, v199
	v_fmamk_f32 v146, v146, 0x3e0293ee, v198
	v_fmamk_f32 v147, v147, 0x3e0293ee, v198
	v_fmamk_f32 v148, v148, 0x3e0293ee, v198
	v_fmamk_f32 v149, v149, 0x3e0293ee, v198
	v_fmamk_f32 v150, v150, 0x3e0293ee, v199
	v_fmamk_f32 v151, v151, 0x3e0293ee, v199
	v_fmamk_f32 v152, v152, 0x3e0293ee, v199
	v_fmamk_f32 v153, v153, 0x3e0293ee, v199
	v_fmamk_f32 v154, v154, 0x3e0293ee, v198
	v_fmamk_f32 v155, v155, 0x3e0293ee, v198
	v_fmamk_f32 v156, v156, 0x3e0293ee, v198
	v_fmamk_f32 v157, v157, 0x3e0293ee, v198
	v_fmamk_f32 v158, v158, 0x3e0293ee, v199
	v_fmamk_f32 v159, v159, 0x3e0293ee, v199
	v_fmamk_f32 v160, v160, 0x3e0293ee, v199
	v_fmamk_f32 v161, v161, 0x3e0293ee, v199
	v_exp_f32_e32 v130, v130
	v_exp_f32_e32 v131, v131
	v_exp_f32_e32 v132, v132
	v_exp_f32_e32 v133, v133
	v_exp_f32_e32 v134, v134
	v_exp_f32_e32 v135, v135
	v_exp_f32_e32 v136, v136
	v_exp_f32_e32 v137, v137
	v_exp_f32_e32 v138, v138
	v_exp_f32_e32 v139, v139
; #define SBAR() __builtin_amdgcn_sched_barrier(0)
; #define PV_STEP(B) do { pv_reads<(B) + 1>(fn, vb); asm volatile("s_waitcnt lgkmcnt(8)" ::: "memory"); SBAR(); pv_mma(o[B], fc, pa0, pa1, pa2, pa3); SBAR(); fc = fn; } while (0)
; __device__ __forceinline__ void finishSM(f32x16& p0, f32x16& p1, float alpha, float& l_reg, bf16x8& pa0, bf16x8& pa1, bf16x8& pa2, bf16x8& pa3) {
;   for (int r = 0; r < 16; ++r) p1[r] = __builtin_amdgcn_exp2f(p1[r]);
;   float ps = 0; for (int r = 0; r < 16; ++r) ps += p0[r]; for (int r = 0; r < 16; ++r) ps += p1[r];
;   { auto rr = __builtin_amdgcn_permlane32_swap(__float_as_uint(ps), __float_as_uint(ps), false, false);
;     ps = __uint_as_float(rr[0]) + __uint_as_float(rr[1]); }
;   l_reg = l_reg * alpha + ps;
;     ...
;   PK4(p0, 0, pa0); PK4(p0, 8, pa1); PK4(p1, 0, pa2); PK4(p1, 8, pa3);
; template <int B> __device__ __forceinline__ void pv_reads(VFrag& f, int vb) {
;   constexpr int base = (B >> 2) * 16384 + (B & 3) * 512;
;   f.l0 = tr_read<base + 0 * 4096>(vb); f.h0 = tr_read<base + 0 * 4096 + 2048>(vb); f.l1 = tr_read<base + 1 * 4096>(vb); f.h1 = tr_read<base + 1 * 4096 + 2048>(vb);
;   f.l2 = tr_read<base + 2 * 4096>(vb); f.h2 = tr_read<base + 2 * 4096 + 2048>(vb); f.l3 = tr_read<base + 3 * 4096>(vb); f.h3 = tr_read<base + 3 * 4096 + 2048>(vb);
; }
; __device__ __forceinline__ void pv_mma(f32x16& od, const VFrag& f, bf16x8 pa0, bf16x8 pa1, bf16x8 pa2, bf16x8 pa3) {
;     ...
;   od = __builtin_amdgcn_mfma_f32_32x32x16_bf16(pa0, PKV(f.l0, f.h0), od, 0, 0, 0);
;   od = __builtin_amdgcn_mfma_f32_32x32x16_bf16(pa1, PKV(f.l1, f.h1), od, 0, 0, 0);
;   od = __builtin_amdgcn_mfma_f32_32x32x16_bf16(pa2, PKV(f.l2, f.h2), od, 0, 0, 0);
;   od = __builtin_amdgcn_mfma_f32_32x32x16_bf16(pa3, PKV(f.l3, f.h3), od, 0, 0, 0);
;     ...
; }
; __device__ __forceinline__ void pv_all(f32x16* o, int vb, bf16x8 pa0, bf16x8 pa1, bf16x8 pa2, bf16x8 pa3) {
;   VFrag fc, fn;
;   pv_reads<0>(fc, vb);
;   PV_STEP(0); PV_STEP(1); PV_STEP(2); PV_STEP(3); PV_STEP(4); PV_STEP(5); PV_STEP(6);
;   asm volatile("s_waitcnt lgkmcnt(0)" ::: "memory"); SBAR(); pv_mma(o[7], fc, pa0, pa1, pa2, pa3);
; }
	v_exp_f32_e32 v140, v140
	v_exp_f32_e32 v141, v141
	v_exp_f32_e32 v142, v142
	v_exp_f32_e32 v143, v143
	v_exp_f32_e32 v144, v144
	v_exp_f32_e32 v145, v145
	v_exp_f32_e32 v146, v146
	v_exp_f32_e32 v147, v147
	v_exp_f32_e32 v148, v148
	v_exp_f32_e32 v149, v149
	v_exp_f32_e32 v150, v150
	v_exp_f32_e32 v151, v151
	v_exp_f32_e32 v152, v152
	v_exp_f32_e32 v153, v153
	v_exp_f32_e32 v154, v154
	v_exp_f32_e32 v155, v155
	v_exp_f32_e32 v156, v156
	v_exp_f32_e32 v157, v157
	v_exp_f32_e32 v158, v158
	v_exp_f32_e32 v159, v159
	v_exp_f32_e32 v160, v160
	v_exp_f32_e32 v161, v161
	v_add_f32_e32 v194, v130, v131
	v_add_f32_e32 v194, v194, v132
	v_add_f32_e32 v194, v194, v133
	v_add_f32_e32 v194, v194, v138
	v_add_f32_e32 v194, v194, v139
	v_add_f32_e32 v194, v194, v140
	v_add_f32_e32 v194, v194, v141
	v_add_f32_e32 v194, v194, v146
	v_add_f32_e32 v194, v194, v147
	v_add_f32_e32 v194, v194, v148
	v_add_f32_e32 v194, v194, v149
	v_add_f32_e32 v194, v194, v154
	v_add_f32_e32 v194, v194, v155
	v_add_f32_e32 v194, v194, v156
	v_add_f32_e32 v194, v194, v157
	v_add_f32_e32 v195, v134, v135
	v_add_f32_e32 v195, v195, v136
	v_add_f32_e32 v195, v195, v137
	v_add_f32_e32 v195, v195, v142
	v_add_f32_e32 v195, v195, v143
	v_add_f32_e32 v195, v195, v144
	v_add_f32_e32 v195, v195, v145
	v_add_f32_e32 v195, v195, v150
	v_add_f32_e32 v195, v195, v151
	v_add_f32_e32 v195, v195, v152
	v_add_f32_e32 v195, v195, v153
	v_add_f32_e32 v195, v195, v158
	v_add_f32_e32 v195, v195, v159
	v_add_f32_e32 v195, v195, v160
	v_add_f32_e32 v195, v195, v161
	v_fma_f32 v250, v250, v236, v194
	v_fma_f32 v234, v234, v240, v195
	v_cvt_pk_bf16_f32 v130, v130, v131
	v_cvt_pk_bf16_f32 v131, v132, v133
	v_cvt_pk_bf16_f32 v132, v138, v139
	v_cvt_pk_bf16_f32 v133, v140, v141
	v_cvt_pk_bf16_f32 v134, v134, v135
	v_cvt_pk_bf16_f32 v135, v136, v137
	v_cvt_pk_bf16_f32 v136, v142, v143
	v_cvt_pk_bf16_f32 v137, v144, v145
	v_cvt_pk_bf16_f32 v138, v146, v147
	v_cvt_pk_bf16_f32 v139, v148, v149
	v_cvt_pk_bf16_f32 v140, v154, v155
	v_cvt_pk_bf16_f32 v141, v156, v157
	v_cvt_pk_bf16_f32 v142, v150, v151
	v_cvt_pk_bf16_f32 v143, v152, v153
	v_cvt_pk_bf16_f32 v144, v158, v159
	v_cvt_pk_bf16_f32 v145, v160, v161
	v_add_u32_e32 v244, s98, v248
	ds_read_b64_tr_b16 v[146:147], v244
	ds_read_b64_tr_b16 v[148:149], v244 offset:4096
	ds_read_b64_tr_b16 v[150:151], v244 offset:8192
	ds_read_b64_tr_b16 v[152:153], v244 offset:12288
	ds_read_b64_tr_b16 v[154:155], v244 offset:256
	ds_read_b64_tr_b16 v[156:157], v244 offset:4352
	ds_read_b64_tr_b16 v[158:159], v244 offset:8448
	ds_read_b64_tr_b16 v[160:161], v244 offset:12544
	ds_read_b64_tr_b16 v[194:195], v244 offset:512
	ds_read_b64_tr_b16 v[196:197], v244 offset:4608
	ds_read_b64_tr_b16 v[198:199], v244 offset:8704
	ds_read_b64_tr_b16 v[200:201], v244 offset:12800
	s_waitcnt vmcnt(0)
	s_barrier
	s_mov_b32 s101, s98
	s_mov_b32 s98, s99
	s_mov_b32 s99, s100
	s_mov_b32 s100, s101
	s_add_u32 s14, s14, 0x40000
	s_addc_u32 s15, s15, 0
	s_add_i32 s13, s13, 1
	s_cmp_eq_u32 s23, s14
	s_cbranch_scc0 .Lat_y_top
	s_waitcnt lgkmcnt(8)
	v_mfma_f32_16x16x32_bf16 v[2:5], v[146:149], v[130:133], v[2:5]
	v_mfma_f32_16x16x32_bf16 v[6:9], v[146:149], v[134:137], v[6:9]
	v_mfma_f32_16x16x32_bf16 v[2:5], v[150:153], v[138:141], v[2:5]
	v_mfma_f32_16x16x32_bf16 v[6:9], v[150:153], v[142:145], v[6:9]
	ds_read_b64_tr_b16 v[146:147], v244 offset:768
	ds_read_b64_tr_b16 v[148:149], v244 offset:4864
	ds_read_b64_tr_b16 v[150:151], v244 offset:8960
	ds_read_b64_tr_b16 v[152:153], v244 offset:13056
	s_waitcnt lgkmcnt(8)
	v_mfma_f32_16x16x32_bf16 v[10:13], v[154:157], v[130:133], v[10:13]
	v_mfma_f32_16x16x32_bf16 v[14:17], v[154:157], v[134:137], v[14:17]
	v_mfma_f32_16x16x32_bf16 v[10:13], v[158:161], v[138:141], v[10:13]
	v_mfma_f32_16x16x32_bf16 v[14:17], v[158:161], v[142:145], v[14:17]
	ds_read_b64_tr_b16 v[154:155], v244 offset:1024
	ds_read_b64_tr_b16 v[156:157], v244 offset:5120
	ds_read_b64_tr_b16 v[158:159], v244 offset:9216
	ds_read_b64_tr_b16 v[160:161], v244 offset:13312
	s_waitcnt lgkmcnt(8)
	v_mfma_f32_16x16x32_bf16 v[114:117], v[194:197], v[130:133], v[114:117]
	v_mfma_f32_16x16x32_bf16 v[118:121], v[194:197], v[134:137], v[118:121]
	v_mfma_f32_16x16x32_bf16 v[114:117], v[198:201], v[138:141], v[114:117]
	v_mfma_f32_16x16x32_bf16 v[118:121], v[198:201], v[142:145], v[118:121]
	ds_read_b64_tr_b16 v[194:195], v244 offset:1280
	ds_read_b64_tr_b16 v[196:197], v244 offset:5376
	ds_read_b64_tr_b16 v[198:199], v244 offset:9472
	ds_read_b64_tr_b16 v[200:201], v244 offset:13568
	s_waitcnt lgkmcnt(8)
	v_mfma_f32_16x16x32_bf16 v[122:125], v[146:149], v[130:133], v[122:125]
	v_mfma_f32_16x16x32_bf16 v[126:129], v[146:149], v[134:137], v[126:129]
	v_mfma_f32_16x16x32_bf16 v[122:125], v[150:153], v[138:141], v[122:125]
	v_mfma_f32_16x16x32_bf16 v[126:129], v[150:153], v[142:145], v[126:129]
	ds_read_b64_tr_b16 v[146:147], v244 offset:1536
	ds_read_b64_tr_b16 v[148:149], v244 offset:5632
	ds_read_b64_tr_b16 v[150:151], v244 offset:9728
	ds_read_b64_tr_b16 v[152:153], v244 offset:13824
	s_waitcnt lgkmcnt(8)
; #define SBAR() __builtin_amdgcn_sched_barrier(0)
; #define PV_STEP(B) do { pv_reads<(B) + 1>(fn, vb); asm volatile("s_waitcnt lgkmcnt(8)" ::: "memory"); SBAR(); pv_mma(o[B], fc, pa0, pa1, pa2, pa3); SBAR(); fc = fn; } while (0)
; __device__ __forceinline__ void pv_mma(f32x16& od, const VFrag& f, bf16x8 pa0, bf16x8 pa1, bf16x8 pa2, bf16x8 pa3) {
;     ...
;   od = __builtin_amdgcn_mfma_f32_32x32x16_bf16(pa0, PKV(f.l0, f.h0), od, 0, 0, 0);
;   od = __builtin_amdgcn_mfma_f32_32x32x16_bf16(pa1, PKV(f.l1, f.h1), od, 0, 0, 0);
;   od = __builtin_amdgcn_mfma_f32_32x32x16_bf16(pa2, PKV(f.l2, f.h2), od, 0, 0, 0);
;   od = __builtin_amdgcn_mfma_f32_32x32x16_bf16(pa3, PKV(f.l3, f.h3), od, 0, 0, 0);
;     ...
; }
; __device__ __forceinline__ void pv_all(f32x16* o, int vb, bf16x8 pa0, bf16x8 pa1, bf16x8 pa2, bf16x8 pa3) {
;   VFrag fc, fn;
;   pv_reads<0>(fc, vb);
;   PV_STEP(0); PV_STEP(1); PV_STEP(2); PV_STEP(3); PV_STEP(4); PV_STEP(5); PV_STEP(6);
;   asm volatile("s_waitcnt lgkmcnt(0)" ::: "memory"); SBAR(); pv_mma(o[7], fc, pa0, pa1, pa2, pa3);
; }
	v_mfma_f32_16x16x32_bf16 v[98:101], v[154:157], v[130:133], v[98:101]
	v_mfma_f32_16x16x32_bf16 v[102:105], v[154:157], v[134:137], v[102:105]
	v_mfma_f32_16x16x32_bf16 v[98:101], v[158:161], v[138:141], v[98:101]
	v_mfma_f32_16x16x32_bf16 v[102:105], v[158:161], v[142:145], v[102:105]
	ds_read_b64_tr_b16 v[154:155], v244 offset:1792
	ds_read_b64_tr_b16 v[156:157], v244 offset:5888
	ds_read_b64_tr_b16 v[158:159], v244 offset:9984
	ds_read_b64_tr_b16 v[160:161], v244 offset:14080
	s_waitcnt lgkmcnt(8)
	v_mfma_f32_16x16x32_bf16 v[106:109], v[194:197], v[130:133], v[106:109]
	v_mfma_f32_16x16x32_bf16 v[110:113], v[194:197], v[134:137], v[110:113]
	v_mfma_f32_16x16x32_bf16 v[106:109], v[198:201], v[138:141], v[106:109]
	v_mfma_f32_16x16x32_bf16 v[110:113], v[198:201], v[142:145], v[110:113]
	ds_read_b64_tr_b16 v[194:195], v244 offset:16384
	ds_read_b64_tr_b16 v[196:197], v244 offset:20480
	ds_read_b64_tr_b16 v[198:199], v244 offset:24576
	ds_read_b64_tr_b16 v[200:201], v244 offset:28672
	s_waitcnt lgkmcnt(8)
	v_mfma_f32_16x16x32_bf16 v[82:85], v[146:149], v[130:133], v[82:85]
	v_mfma_f32_16x16x32_bf16 v[86:89], v[146:149], v[134:137], v[86:89]
	v_mfma_f32_16x16x32_bf16 v[82:85], v[150:153], v[138:141], v[82:85]
	v_mfma_f32_16x16x32_bf16 v[86:89], v[150:153], v[142:145], v[86:89]
	ds_read_b64_tr_b16 v[146:147], v244 offset:16640
	ds_read_b64_tr_b16 v[148:149], v244 offset:20736
	ds_read_b64_tr_b16 v[150:151], v244 offset:24832
	ds_read_b64_tr_b16 v[152:153], v244 offset:28928
	s_waitcnt lgkmcnt(8)
	v_mfma_f32_16x16x32_bf16 v[90:93], v[154:157], v[130:133], v[90:93]
	v_mfma_f32_16x16x32_bf16 v[94:97], v[154:157], v[134:137], v[94:97]
	v_mfma_f32_16x16x32_bf16 v[90:93], v[158:161], v[138:141], v[90:93]
	v_mfma_f32_16x16x32_bf16 v[94:97], v[158:161], v[142:145], v[94:97]
	ds_read_b64_tr_b16 v[154:155], v244 offset:16896
	ds_read_b64_tr_b16 v[156:157], v244 offset:20992
	ds_read_b64_tr_b16 v[158:159], v244 offset:25088
	ds_read_b64_tr_b16 v[160:161], v244 offset:29184
	s_waitcnt lgkmcnt(8)
	v_mfma_f32_16x16x32_bf16 v[66:69], v[194:197], v[130:133], v[66:69]
	v_mfma_f32_16x16x32_bf16 v[70:73], v[194:197], v[134:137], v[70:73]
	v_mfma_f32_16x16x32_bf16 v[66:69], v[198:201], v[138:141], v[66:69]
	v_mfma_f32_16x16x32_bf16 v[70:73], v[198:201], v[142:145], v[70:73]
	ds_read_b64_tr_b16 v[194:195], v244 offset:17152
	ds_read_b64_tr_b16 v[196:197], v244 offset:21248
	ds_read_b64_tr_b16 v[198:199], v244 offset:25344
	ds_read_b64_tr_b16 v[200:201], v244 offset:29440
	s_waitcnt lgkmcnt(8)
	v_mfma_f32_16x16x32_bf16 v[74:77], v[146:149], v[130:133], v[74:77]
	v_mfma_f32_16x16x32_bf16 v[78:81], v[146:149], v[134:137], v[78:81]
	v_mfma_f32_16x16x32_bf16 v[74:77], v[150:153], v[138:141], v[74:77]
	v_mfma_f32_16x16x32_bf16 v[78:81], v[150:153], v[142:145], v[78:81]
	ds_read_b64_tr_b16 v[146:147], v244 offset:17408
	ds_read_b64_tr_b16 v[148:149], v244 offset:21504
	ds_read_b64_tr_b16 v[150:151], v244 offset:25600
	ds_read_b64_tr_b16 v[152:153], v244 offset:29696
	s_waitcnt lgkmcnt(8)
	v_mfma_f32_16x16x32_bf16 v[50:53], v[154:157], v[130:133], v[50:53]
	v_mfma_f32_16x16x32_bf16 v[54:57], v[154:157], v[134:137], v[54:57]
	v_mfma_f32_16x16x32_bf16 v[50:53], v[158:161], v[138:141], v[50:53]
	v_mfma_f32_16x16x32_bf16 v[54:57], v[158:161], v[142:145], v[54:57]
	ds_read_b64_tr_b16 v[154:155], v244 offset:17664
	ds_read_b64_tr_b16 v[156:157], v244 offset:21760
	ds_read_b64_tr_b16 v[158:159], v244 offset:25856
	ds_read_b64_tr_b16 v[160:161], v244 offset:29952
	s_waitcnt lgkmcnt(8)
	v_mfma_f32_16x16x32_bf16 v[58:61], v[194:197], v[130:133], v[58:61]
	v_mfma_f32_16x16x32_bf16 v[62:65], v[194:197], v[134:137], v[62:65]
	v_mfma_f32_16x16x32_bf16 v[58:61], v[198:201], v[138:141], v[58:61]
	v_mfma_f32_16x16x32_bf16 v[62:65], v[198:201], v[142:145], v[62:65]
	ds_read_b64_tr_b16 v[194:195], v244 offset:17920
	ds_read_b64_tr_b16 v[196:197], v244 offset:22016
	ds_read_b64_tr_b16 v[198:199], v244 offset:26112
	ds_read_b64_tr_b16 v[200:201], v244 offset:30208
	s_waitcnt lgkmcnt(8)
	v_mfma_f32_16x16x32_bf16 v[34:37], v[146:149], v[130:133], v[34:37]
	v_mfma_f32_16x16x32_bf16 v[38:41], v[146:149], v[134:137], v[38:41]
	v_mfma_f32_16x16x32_bf16 v[34:37], v[150:153], v[138:141], v[34:37]
	v_mfma_f32_16x16x32_bf16 v[38:41], v[150:153], v[142:145], v[38:41]
	ds_read_b64_tr_b16 v[146:147], v244 offset:18176
	ds_read_b64_tr_b16 v[148:149], v244 offset:22272
	ds_read_b64_tr_b16 v[150:151], v244 offset:26368
	ds_read_b64_tr_b16 v[152:153], v244 offset:30464
	s_waitcnt lgkmcnt(8)
	v_mfma_f32_16x16x32_bf16 v[42:45], v[154:157], v[130:133], v[42:45]
	v_mfma_f32_16x16x32_bf16 v[46:49], v[154:157], v[134:137], v[46:49]
	v_mfma_f32_16x16x32_bf16 v[42:45], v[158:161], v[138:141], v[42:45]
	v_mfma_f32_16x16x32_bf16 v[46:49], v[158:161], v[142:145], v[46:49]
	s_waitcnt lgkmcnt(4)
	v_mfma_f32_16x16x32_bf16 v[18:21], v[194:197], v[130:133], v[18:21]
	v_mfma_f32_16x16x32_bf16 v[22:25], v[194:197], v[134:137], v[22:25]
	v_mfma_f32_16x16x32_bf16 v[18:21], v[198:201], v[138:141], v[18:21]
	v_mfma_f32_16x16x32_bf16 v[22:25], v[198:201], v[142:145], v[22:25]
	s_waitcnt lgkmcnt(0)
	v_mfma_f32_16x16x32_bf16 v[26:29], v[146:149], v[130:133], v[26:29]
	v_mfma_f32_16x16x32_bf16 v[30:33], v[146:149], v[134:137], v[30:33]
	v_mfma_f32_16x16x32_bf16 v[26:29], v[150:153], v[138:141], v[26:29]
	v_mfma_f32_16x16x32_bf16 v[30:33], v[150:153], v[142:145], v[30:33]
